# v26 + static wave priority: second-slot workgroups (blockIdx >= 256) run at s_setprio 1 for the whole kernel, per-segment priority toggles in the GEMM loops replaced by s_nop
# baseline (speedup 1.0000x reference)
.LBB0_56:
	s_or_b64 exec, exec, s[6:7]
	v_writelane_b32 v237, s24, 31
	s_barrier
	v_readlane_b32 s98, v237, 31
	s_cmp_lt_u32 s98, 0x100
	s_cbranch_scc1 .Lmy_prio_skip
	s_setprio 1
.Lmy_prio_skip:
	s_getreg_b32 s4, hwreg(HW_REG_XCC_ID, 0, 4)
	v_writelane_b32 v237, s25, 32
	s_and_b32 s4, s4, 15
	v_writelane_b32 v237, s4, 33
	s_mov_b64 s[6:7], exec
	v_readlane_b32 s4, v237, 1
	v_readlane_b32 s5, v237, 2
	s_and_b64 s[4:5], s[6:7], s[4:5]
	s_mov_b64 exec, s[4:5]
	s_cbranch_execz .LBB0_59
	s_mov_b64 s[12:13], exec
	v_mbcnt_lo_u32_b32 v0, s12, 0
	v_mbcnt_hi_u32_b32 v0, s13, v0
	v_cmp_eq_u32_e32 vcc, 0, v0
	s_and_b64 s[4:5], exec, vcc
	s_mov_b64 exec, s[4:5]
	s_cbranch_execz .LBB0_59
	v_readlane_b32 s4, v237, 33
	s_lshl_b32 s4, s4, 8
	s_bcnt1_i32_b64 s5, s[12:13]
	v_mov_b32_e32 v0, s4
	v_mov_b32_e32 v1, s5
	v_readlane_b32 s4, v237, 3
	v_readlane_b32 s5, v237, 4
	s_nop 4
	global_atomic_add v0, v1, s[4:5] offset:1024

.LBB0_67:
	s_waitcnt vmcnt(15)
	v_lshl_add_u64 v[60:61], v[130:131], 1, s[88:89]
	global_load_dwordx4 v[60:63], v[60:61], off
	ds_read_b128 v[170:173], v132 offset:40960
	ds_read_b128 v[174:177], v132 offset:43520
	ds_read_b128 v[178:181], v133 offset:61440
	ds_read_b128 v[182:185], v133 offset:64000
	ds_read_b128 v[186:189], v132 offset:46080
	ds_read_b128 v[190:193], v132 offset:48640
	ds_read_b128 v[194:197], v150 offset:5120
	ds_read_b128 v[198:201], v150 offset:7680
	s_nop 0
	s_waitcnt lgkmcnt(5)
	v_mfma_f32_16x16x32_bf16 v[64:67], v[178:181], v[170:173], v[64:67]
	v_mfma_f32_16x16x32_bf16 v[68:71], v[178:181], v[174:177], v[68:71]
	s_waitcnt lgkmcnt(3)
	v_mfma_f32_16x16x32_bf16 v[72:75], v[178:181], v[186:189], v[72:75]
	s_waitcnt lgkmcnt(2)
	v_mfma_f32_16x16x32_bf16 v[76:79], v[178:181], v[190:193], v[76:79]
	v_mfma_f32_16x16x32_bf16 v[80:83], v[182:185], v[170:173], v[80:83]
	v_mfma_f32_16x16x32_bf16 v[84:87], v[182:185], v[174:177], v[84:87]
	v_mfma_f32_16x16x32_bf16 v[88:91], v[182:185], v[186:189], v[88:91]
	v_mfma_f32_16x16x32_bf16 v[92:95], v[182:185], v[190:193], v[92:95]
	s_waitcnt lgkmcnt(1)
	v_mfma_f32_16x16x32_bf16 v[178:181], v[194:197], v[170:173], v[96:99]
	v_mfma_f32_16x16x32_bf16 v[182:185], v[194:197], v[174:177], v[100:103]
	v_mfma_f32_16x16x32_bf16 v[202:205], v[194:197], v[186:189], v[104:107]
	v_mfma_f32_16x16x32_bf16 v[194:197], v[194:197], v[190:193], v[108:111]
	s_waitcnt lgkmcnt(0)
	v_mfma_f32_16x16x32_bf16 v[170:173], v[198:201], v[170:173], v[112:115]
	v_mfma_f32_16x16x32_bf16 v[174:177], v[198:201], v[174:177], v[116:119]
	v_mfma_f32_16x16x32_bf16 v[186:189], v[198:201], v[186:189], v[120:123]
	v_mfma_f32_16x16x32_bf16 v[190:193], v[198:201], v[190:193], v[124:127]
	s_nop 0
	ds_read_b128 v[198:201], v132 offset:41024
	ds_read_b128 v[206:209], v132 offset:43584
	ds_read_b128 v[96:99], v133 offset:61504
	ds_read_b128 v[210:213], v133 offset:64064
	ds_read_b128 v[214:217], v132 offset:46144
	ds_read_b128 v[218:221], v132 offset:48704
	ds_read_b128 v[222:225], v151 offset:5120
	ds_read_b128 v[226:229], v151 offset:7680
	s_nop 0
	s_waitcnt lgkmcnt(5)
	v_mfma_f32_16x16x32_bf16 v[124:127], v[96:99], v[198:201], v[64:67]
	v_mfma_f32_16x16x32_bf16 v[120:123], v[96:99], v[206:209], v[68:71]
	s_waitcnt lgkmcnt(3)
	v_mfma_f32_16x16x32_bf16 v[116:119], v[96:99], v[214:217], v[72:75]
	s_waitcnt lgkmcnt(2)
	v_mfma_f32_16x16x32_bf16 v[112:115], v[96:99], v[218:221], v[76:79]
	v_mfma_f32_16x16x32_bf16 v[108:111], v[210:213], v[198:201], v[80:83]
	v_mfma_f32_16x16x32_bf16 v[104:107], v[210:213], v[206:209], v[84:87]
	v_mfma_f32_16x16x32_bf16 v[100:103], v[210:213], v[214:217], v[88:91]
	v_mfma_f32_16x16x32_bf16 v[96:99], v[210:213], v[218:221], v[92:95]
	s_waitcnt lgkmcnt(1)
	v_mfma_f32_16x16x32_bf16 v[92:95], v[222:225], v[198:201], v[178:181]
	v_mfma_f32_16x16x32_bf16 v[88:91], v[222:225], v[206:209], v[182:185]
	v_mfma_f32_16x16x32_bf16 v[84:87], v[222:225], v[214:217], v[202:205]
	v_mfma_f32_16x16x32_bf16 v[80:83], v[222:225], v[218:221], v[194:197]
	s_waitcnt lgkmcnt(0)
	v_mfma_f32_16x16x32_bf16 v[76:79], v[226:229], v[198:201], v[170:173]
	v_mfma_f32_16x16x32_bf16 v[72:75], v[226:229], v[206:209], v[174:177]
	v_mfma_f32_16x16x32_bf16 v[68:71], v[226:229], v[214:217], v[186:189]
	v_mfma_f32_16x16x32_bf16 v[64:67], v[226:229], v[218:221], v[190:193]
	s_nop 0
	s_add_i32 s31, s31, 2
	s_addk_i32 s30, 0x80
	s_addk_i32 s29, 0x80
	v_add_u32_e32 v161, 0x80, v161
	v_add_u32_e32 v162, 0x80, v162
	v_add_u32_e32 v163, 0x80, v163
	v_add_u32_e32 v164, 0x80, v164
	s_addk_i32 s27, 0x80
	v_add_u32_e32 v165, 0x80, v165
	v_add_u32_e32 v166, 0x80, v166
	v_add_u32_e32 v167, 0x80, v167
	v_add_u32_e32 v168, 0x80, v168
	s_and_b64 vcc, exec, s[16:17]
	s_cbranch_vccnz .LBB0_86

.LBB0_76:
	s_nop 0
	v_lshl_add_u64 v[56:57], v[130:131], 1, s[88:89]
	global_load_dwordx4 v[56:59], v[56:57], off
	ds_read_b128 v[170:173], v132
	ds_read_b128 v[174:177], v132 offset:2560
	ds_read_b128 v[178:181], v133 offset:20480
	ds_read_b128 v[182:185], v133 offset:23040
	ds_read_b128 v[186:189], v132 offset:5120
	ds_read_b128 v[190:193], v132 offset:7680
	ds_read_b128 v[194:197], v133 offset:25600
	ds_read_b128 v[198:201], v133 offset:28160
	s_nop 0
	s_waitcnt lgkmcnt(5)
	v_mfma_f32_16x16x32_bf16 v[124:127], v[178:181], v[170:173], v[124:127]
	v_mfma_f32_16x16x32_bf16 v[120:123], v[178:181], v[174:177], v[120:123]
	s_waitcnt lgkmcnt(3)
	v_mfma_f32_16x16x32_bf16 v[116:119], v[178:181], v[186:189], v[116:119]
	s_waitcnt lgkmcnt(2)
	v_mfma_f32_16x16x32_bf16 v[112:115], v[178:181], v[190:193], v[112:115]
	v_mfma_f32_16x16x32_bf16 v[108:111], v[182:185], v[170:173], v[108:111]
	v_mfma_f32_16x16x32_bf16 v[104:107], v[182:185], v[174:177], v[104:107]
	v_mfma_f32_16x16x32_bf16 v[100:103], v[182:185], v[186:189], v[100:103]
	v_mfma_f32_16x16x32_bf16 v[96:99], v[182:185], v[190:193], v[96:99]
	s_waitcnt lgkmcnt(1)
	v_mfma_f32_16x16x32_bf16 v[178:181], v[194:197], v[170:173], v[92:95]
	v_mfma_f32_16x16x32_bf16 v[182:185], v[194:197], v[174:177], v[88:91]
	v_mfma_f32_16x16x32_bf16 v[202:205], v[194:197], v[186:189], v[84:87]
	v_mfma_f32_16x16x32_bf16 v[194:197], v[194:197], v[190:193], v[80:83]
	s_waitcnt lgkmcnt(0)
	v_mfma_f32_16x16x32_bf16 v[170:173], v[198:201], v[170:173], v[76:79]
	v_mfma_f32_16x16x32_bf16 v[174:177], v[198:201], v[174:177], v[72:75]
	v_mfma_f32_16x16x32_bf16 v[186:189], v[198:201], v[186:189], v[68:71]
	v_mfma_f32_16x16x32_bf16 v[190:193], v[198:201], v[190:193], v[64:67]
	s_nop 0
	ds_read_b128 v[198:201], v132 offset:64
	ds_read_b128 v[206:209], v132 offset:2624
	ds_read_b128 v[76:79], v133 offset:20544
	ds_read_b128 v[92:95], v133 offset:23104
	ds_read_b128 v[210:213], v132 offset:5184
	ds_read_b128 v[214:217], v132 offset:7744
	ds_read_b128 v[218:221], v133 offset:25664
	ds_read_b128 v[222:225], v133 offset:28224
	s_nop 0
	s_waitcnt lgkmcnt(5)
	v_mfma_f32_16x16x32_bf16 v[64:67], v[76:79], v[198:201], v[124:127]
	v_mfma_f32_16x16x32_bf16 v[68:71], v[76:79], v[206:209], v[120:123]
	s_waitcnt lgkmcnt(3)
	v_mfma_f32_16x16x32_bf16 v[72:75], v[76:79], v[210:213], v[116:119]
	s_waitcnt lgkmcnt(2)
	v_mfma_f32_16x16x32_bf16 v[76:79], v[76:79], v[214:217], v[112:115]
	v_mfma_f32_16x16x32_bf16 v[80:83], v[92:95], v[198:201], v[108:111]
	v_mfma_f32_16x16x32_bf16 v[84:87], v[92:95], v[206:209], v[104:107]
	v_mfma_f32_16x16x32_bf16 v[88:91], v[92:95], v[210:213], v[100:103]
	v_mfma_f32_16x16x32_bf16 v[92:95], v[92:95], v[214:217], v[96:99]
	s_waitcnt lgkmcnt(1)
	v_mfma_f32_16x16x32_bf16 v[96:99], v[218:221], v[198:201], v[178:181]
	v_mfma_f32_16x16x32_bf16 v[100:103], v[218:221], v[206:209], v[182:185]
	v_mfma_f32_16x16x32_bf16 v[104:107], v[218:221], v[210:213], v[202:205]
	v_mfma_f32_16x16x32_bf16 v[108:111], v[218:221], v[214:217], v[194:197]
	s_waitcnt lgkmcnt(0)
	v_mfma_f32_16x16x32_bf16 v[112:115], v[222:225], v[198:201], v[170:173]
	v_mfma_f32_16x16x32_bf16 v[116:119], v[222:225], v[206:209], v[174:177]
	v_mfma_f32_16x16x32_bf16 v[120:123], v[222:225], v[210:213], v[186:189]
	v_mfma_f32_16x16x32_bf16 v[124:127], v[222:225], v[214:217], v[190:193]
	s_nop 0
	s_cmp_gt_u32 s31, 13
	s_cselect_b64 s[16:17], -1, 0
	s_cmp_lt_u32 s31, 14
	s_cselect_b64 s[4:5], -1, 0
	s_or_b64 s[4:5], s[14:15], s[4:5]
	s_andn2_b64 vcc, exec, s[4:5]
	s_barrier
	s_cbranch_vccnz .LBB0_78
	s_waitcnt vmcnt(15)
	ds_write_b128 v146, v[4:7]
	s_waitcnt vmcnt(14)
	ds_write_b128 v146, v[12:15] offset:20480
	s_waitcnt vmcnt(13)
	ds_write_b128 v147, v[20:23]
	s_waitcnt vmcnt(12)
	ds_write_b128 v147, v[32:35] offset:20480
	s_waitcnt vmcnt(11)
	ds_write_b128 v148, v[40:43]
	s_waitcnt vmcnt(10)
	ds_write_b128 v148, v[48:51] offset:20480
	s_waitcnt vmcnt(9)
	ds_write_b128 v149, v[52:55]
	s_waitcnt vmcnt(8)
	ds_write_b128 v149, v[60:63] offset:20480

.LBB0_144:
	s_or_b64 exec, exec, s[0:1]
	v_bfe_u32 v104, v39, 4, 2
	v_and_or_b32 v105, v39, 15, v40
	v_lshlrev_b32_e32 v0, 4, v104
	v_and_b32_e32 v6, 0x4f, v39
	v_mad_u64_u32 v[2:3], s[0:1], v105, s24, v[0:1]
	v_mul_u32_u24_e32 v3, 0x50, v6
	s_waitcnt lgkmcnt(0)
	s_barrier
	v_lshl_add_u32 v0, v3, 1, v0
	ds_read_b128 v[6:9], v2
	ds_read_b128 v[10:13], v2 offset:2560
	ds_read_b128 v[14:17], v0 offset:20480
	ds_read_b128 v[18:21], v0 offset:23040
	ds_read_b128 v[22:25], v2 offset:5120
	ds_read_b128 v[26:29], v2 offset:7680
	ds_read_b128 v[30:33], v0 offset:25600
	ds_read_b128 v[34:37], v0 offset:28160
	v_and_b32_e32 v39, 64, v39
	s_nop 0
	s_waitcnt lgkmcnt(5)
	v_mfma_f32_16x16x32_bf16 v[40:43], v[14:17], v[6:9], 0
	v_mfma_f32_16x16x32_bf16 v[44:47], v[14:17], v[10:13], 0
	s_waitcnt lgkmcnt(3)
	v_mfma_f32_16x16x32_bf16 v[48:51], v[14:17], v[22:25], 0
	s_waitcnt lgkmcnt(2)
	v_mfma_f32_16x16x32_bf16 v[14:17], v[14:17], v[26:29], 0
	v_mfma_f32_16x16x32_bf16 v[52:55], v[18:21], v[6:9], 0
	v_mfma_f32_16x16x32_bf16 v[56:59], v[18:21], v[10:13], 0
	v_mfma_f32_16x16x32_bf16 v[60:63], v[18:21], v[22:25], 0
	v_mfma_f32_16x16x32_bf16 v[18:21], v[18:21], v[26:29], 0
	s_waitcnt lgkmcnt(1)
	v_mfma_f32_16x16x32_bf16 v[64:67], v[30:33], v[6:9], 0
	v_mfma_f32_16x16x32_bf16 v[68:71], v[30:33], v[10:13], 0
	v_mfma_f32_16x16x32_bf16 v[72:75], v[30:33], v[22:25], 0
	v_mfma_f32_16x16x32_bf16 v[30:33], v[30:33], v[26:29], 0
	s_waitcnt lgkmcnt(0)
	v_mfma_f32_16x16x32_bf16 v[6:9], v[34:37], v[6:9], 0
	v_mfma_f32_16x16x32_bf16 v[10:13], v[34:37], v[10:13], 0
	v_mfma_f32_16x16x32_bf16 v[22:25], v[34:37], v[22:25], 0
	v_mfma_f32_16x16x32_bf16 v[26:29], v[34:37], v[26:29], 0
	s_nop 0
	ds_read_b128 v[34:37], v2 offset:64
	ds_read_b128 v[76:79], v2 offset:2624
	ds_read_b128 v[80:83], v0 offset:20544
	ds_read_b128 v[84:87], v0 offset:23104
	ds_read_b128 v[88:91], v2 offset:5184
	ds_read_b128 v[92:95], v2 offset:7744
	ds_read_b128 v[96:99], v0 offset:25664
	ds_read_b128 v[100:103], v0 offset:28224
	s_nop 0
	s_waitcnt lgkmcnt(5)
	v_mfma_f32_16x16x32_bf16 v[40:43], v[80:83], v[34:37], v[40:43]
	v_mfma_f32_16x16x32_bf16 v[44:47], v[80:83], v[76:79], v[44:47]
	s_waitcnt lgkmcnt(3)
	v_mfma_f32_16x16x32_bf16 v[48:51], v[80:83], v[88:91], v[48:51]
	s_waitcnt lgkmcnt(2)
	v_mfma_f32_16x16x32_bf16 v[14:17], v[80:83], v[92:95], v[14:17]
	v_mfma_f32_16x16x32_bf16 v[52:55], v[84:87], v[34:37], v[52:55]
	v_mfma_f32_16x16x32_bf16 v[56:59], v[84:87], v[76:79], v[56:59]
	v_mfma_f32_16x16x32_bf16 v[60:63], v[84:87], v[88:91], v[60:63]
	v_mfma_f32_16x16x32_bf16 v[18:21], v[84:87], v[92:95], v[18:21]
	s_waitcnt lgkmcnt(1)
	v_mfma_f32_16x16x32_bf16 v[64:67], v[96:99], v[34:37], v[64:67]
	v_mfma_f32_16x16x32_bf16 v[68:71], v[96:99], v[76:79], v[68:71]
	v_mfma_f32_16x16x32_bf16 v[72:75], v[96:99], v[88:91], v[72:75]
	v_mfma_f32_16x16x32_bf16 v[30:33], v[96:99], v[92:95], v[30:33]
	s_waitcnt lgkmcnt(0)
	v_mfma_f32_16x16x32_bf16 v[6:9], v[100:103], v[34:37], v[6:9]
	v_mfma_f32_16x16x32_bf16 v[10:13], v[100:103], v[76:79], v[10:13]
	v_mfma_f32_16x16x32_bf16 v[22:25], v[100:103], v[88:91], v[22:25]
	v_mfma_f32_16x16x32_bf16 v[26:29], v[100:103], v[92:95], v[26:29]
	s_nop 0
	v_lshlrev_b64 v[2:3], 15, v[4:5]
	v_lshlrev_b32_e32 v0, 1, v39
	v_lshlrev_b32_e32 v34, 7, v105
	v_lshl_add_u64 v[2:3], s[58:59], 0, v[2:3]
	v_lshl_or_b32 v0, v104, 3, v0
	v_cvt_pk_bf16_f32 v4, v40, v41
	v_or_b32_e32 v40, 0x800, v34
	v_lshl_add_u64 v[2:3], v[2:3], 0, v[0:1]
	v_ashrrev_i32_e32 v35, 31, v34
	v_ashrrev_i32_e32 v41, 31, v40
	v_cvt_pk_bf16_f32 v5, v42, v43
	v_lshl_add_u64 v[36:37], v[34:35], 1, v[2:3]
	v_lshlrev_b64 v[40:41], 1, v[40:41]
	global_store_dwordx2 v[36:37], v[4:5], off
	v_cvt_pk_bf16_f32 v4, v44, v45
	v_cvt_pk_bf16_f32 v5, v46, v47
	v_lshl_add_u64 v[42:43], v[2:3], 0, v[40:41]
	global_store_dwordx2 v[42:43], v[4:5], off
	v_or_b32_e32 v42, 0x1000, v34
	v_ashrrev_i32_e32 v43, 31, v42
	v_lshlrev_b64 v[42:43], 1, v[42:43]
	v_cvt_pk_bf16_f32 v4, v48, v49
	v_cvt_pk_bf16_f32 v5, v50, v51
	v_lshl_add_u64 v[44:45], v[2:3], 0, v[42:43]
	global_store_dwordx2 v[44:45], v[4:5], off
	v_cvt_pk_bf16_f32 v4, v14, v15
	v_or_b32_e32 v14, 0x1800, v34
	v_ashrrev_i32_e32 v15, 31, v14
	v_lshlrev_b64 v[14:15], 1, v[14:15]
	v_cvt_pk_bf16_f32 v5, v16, v17
	v_lshl_add_u64 v[16:17], v[2:3], 0, v[14:15]
	global_store_dwordx2 v[16:17], v[4:5], off
	v_lshl_add_u64 v[4:5], v[2:3], 0, 32
	v_cvt_pk_bf16_f32 v16, v52, v53
	v_cvt_pk_bf16_f32 v17, v54, v55
	global_store_dwordx2 v[36:37], v[16:17], off offset:32
	v_cvt_pk_bf16_f32 v16, v56, v57
	v_cvt_pk_bf16_f32 v17, v58, v59
	v_lshl_add_u64 v[34:35], v[4:5], 0, v[40:41]
	global_store_dwordx2 v[34:35], v[16:17], off
	v_cvt_pk_bf16_f32 v16, v60, v61
	v_cvt_pk_bf16_f32 v17, v62, v63
	v_lshl_add_u64 v[34:35], v[4:5], 0, v[42:43]
	global_store_dwordx2 v[34:35], v[16:17], off
	v_cvt_pk_bf16_f32 v16, v18, v19
	v_cvt_pk_bf16_f32 v17, v20, v21
	v_lshl_add_u64 v[4:5], v[4:5], 0, v[14:15]
	global_store_dwordx2 v[4:5], v[16:17], off
	v_lshl_add_u64 v[4:5], v[2:3], 0, 64
	v_cvt_pk_bf16_f32 v16, v64, v65
	v_cvt_pk_bf16_f32 v17, v66, v67
	global_store_dwordx2 v[36:37], v[16:17], off offset:64
	v_cvt_pk_bf16_f32 v16, v68, v69
	v_cvt_pk_bf16_f32 v17, v70, v71
	v_lshl_add_u64 v[18:19], v[4:5], 0, v[40:41]
	global_store_dwordx2 v[18:19], v[16:17], off
	v_cvt_pk_bf16_f32 v16, v72, v73
	v_cvt_pk_bf16_f32 v17, v74, v75
	v_lshl_add_u64 v[18:19], v[4:5], 0, v[42:43]
	global_store_dwordx2 v[18:19], v[16:17], off
	v_cvt_pk_bf16_f32 v16, v30, v31
	v_cvt_pk_bf16_f32 v17, v32, v33
	v_lshl_add_u64 v[4:5], v[4:5], 0, v[14:15]
	global_store_dwordx2 v[4:5], v[16:17], off
	v_lshl_add_u64 v[2:3], v[2:3], 0, s[14:15]
	v_cvt_pk_bf16_f32 v4, v6, v7
	v_cvt_pk_bf16_f32 v5, v8, v9
	global_store_dwordx2 v[36:37], v[4:5], off offset:96
	v_cvt_pk_bf16_f32 v4, v10, v11
	v_cvt_pk_bf16_f32 v5, v12, v13
	v_lshl_add_u64 v[6:7], v[2:3], 0, v[40:41]
	global_store_dwordx2 v[6:7], v[4:5], off
	v_cvt_pk_bf16_f32 v4, v22, v23
	v_cvt_pk_bf16_f32 v5, v24, v25
	v_lshl_add_u64 v[6:7], v[2:3], 0, v[42:43]
	s_add_i32 s16, s16, s90
	s_add_i32 s20, s20, s21
	global_store_dwordx2 v[6:7], v[4:5], off
	v_cvt_pk_bf16_f32 v4, v26, v27
	v_cvt_pk_bf16_f32 v5, v28, v29
	v_lshl_add_u64 v[2:3], v[2:3], 0, v[14:15]
	s_cmpk_gt_i32 s16, 0x7ff
	global_store_dwordx2 v[2:3], v[4:5], off
	s_cbranch_scc1 .LBB0_149

.LBB0_395:
	s_waitcnt vmcnt(15)
	v_lshl_add_u64 v[60:61], v[130:131], 1, s[10:11]
	global_load_dwordx4 v[60:63], v[60:61], off
	ds_read_b128 v[162:165], v134 offset:40960
	ds_read_b128 v[166:169], v134 offset:43520
	ds_read_b128 v[170:173], v135 offset:61440
	ds_read_b128 v[174:177], v135 offset:64000
	ds_read_b128 v[178:181], v134 offset:46080
	ds_read_b128 v[182:185], v134 offset:48640
	ds_read_b128 v[186:189], v149
	ds_read_b128 v[190:193], v150
	s_nop 0
	s_waitcnt lgkmcnt(5)
	v_mfma_f32_16x16x32_bf16 v[64:67], v[170:173], v[162:165], v[64:67]
	v_mfma_f32_16x16x32_bf16 v[68:71], v[170:173], v[166:169], v[68:71]
	s_waitcnt lgkmcnt(3)
	v_mfma_f32_16x16x32_bf16 v[72:75], v[170:173], v[178:181], v[72:75]
	s_waitcnt lgkmcnt(2)
	v_mfma_f32_16x16x32_bf16 v[76:79], v[170:173], v[182:185], v[76:79]
	v_mfma_f32_16x16x32_bf16 v[80:83], v[174:177], v[162:165], v[80:83]
	v_mfma_f32_16x16x32_bf16 v[84:87], v[174:177], v[166:169], v[84:87]
	v_mfma_f32_16x16x32_bf16 v[88:91], v[174:177], v[178:181], v[88:91]
	s_waitcnt lgkmcnt(1)
	v_mfma_f32_16x16x32_bf16 v[96:99], v[186:189], v[162:165], v[96:99]
	v_mfma_f32_16x16x32_bf16 v[104:107], v[186:189], v[178:181], v[104:107]
	v_mfma_f32_16x16x32_bf16 v[170:173], v[174:177], v[182:185], v[92:95]
	v_mfma_f32_16x16x32_bf16 v[174:177], v[186:189], v[166:169], v[100:103]
	v_mfma_f32_16x16x32_bf16 v[186:189], v[186:189], v[182:185], v[108:111]
	s_waitcnt lgkmcnt(0)
	v_mfma_f32_16x16x32_bf16 v[162:165], v[190:193], v[162:165], v[112:115]
	v_mfma_f32_16x16x32_bf16 v[166:169], v[190:193], v[166:169], v[116:119]
	v_mfma_f32_16x16x32_bf16 v[178:181], v[190:193], v[178:181], v[120:123]
	v_mfma_f32_16x16x32_bf16 v[182:185], v[190:193], v[182:185], v[124:127]
	s_nop 0
	ds_read_b128 v[190:193], v134 offset:41024
	ds_read_b128 v[194:197], v134 offset:43584
	ds_read_b128 v[92:95], v135 offset:61504
	ds_read_b128 v[112:115], v135 offset:64064
	ds_read_b128 v[198:201], v134 offset:46144
	ds_read_b128 v[202:205], v134 offset:48704
	ds_read_b128 v[206:209], v151
	ds_read_b128 v[210:213], v152
	s_nop 0
	s_waitcnt lgkmcnt(5)
	v_mfma_f32_16x16x32_bf16 v[124:127], v[92:95], v[190:193], v[64:67]
	v_mfma_f32_16x16x32_bf16 v[116:119], v[92:95], v[194:197], v[68:71]
	s_waitcnt lgkmcnt(3)
	v_mfma_f32_16x16x32_bf16 v[108:111], v[92:95], v[198:201], v[72:75]
	s_waitcnt lgkmcnt(2)
	v_mfma_f32_16x16x32_bf16 v[100:103], v[92:95], v[202:205], v[76:79]
	v_mfma_f32_16x16x32_bf16 v[92:95], v[112:115], v[190:193], v[80:83]
	v_mfma_f32_16x16x32_bf16 v[84:87], v[112:115], v[194:197], v[84:87]
	v_mfma_f32_16x16x32_bf16 v[76:79], v[112:115], v[198:201], v[88:91]
	v_mfma_f32_16x16x32_bf16 v[68:71], v[112:115], v[202:205], v[170:173]
	s_waitcnt lgkmcnt(1)
	v_mfma_f32_16x16x32_bf16 v[120:123], v[206:209], v[190:193], v[96:99]
	v_mfma_f32_16x16x32_bf16 v[112:115], v[206:209], v[194:197], v[174:177]
	v_mfma_f32_16x16x32_bf16 v[104:107], v[206:209], v[198:201], v[104:107]
	v_mfma_f32_16x16x32_bf16 v[96:99], v[206:209], v[202:205], v[186:189]
	s_waitcnt lgkmcnt(0)
	v_mfma_f32_16x16x32_bf16 v[88:91], v[210:213], v[190:193], v[162:165]
	v_mfma_f32_16x16x32_bf16 v[80:83], v[210:213], v[194:197], v[166:169]
	v_mfma_f32_16x16x32_bf16 v[72:75], v[210:213], v[198:201], v[178:181]
	v_mfma_f32_16x16x32_bf16 v[64:67], v[210:213], v[202:205], v[182:185]
	s_nop 0
	s_add_i32 s21, s21, 2
	v_add_u32_e32 v144, 0x80, v144
	v_add_u32_e32 v143, 0x80, v143
	v_add_u32_e32 v142, 0x80, v142
	s_andn2_b64 vcc, exec, s[6:7]
	v_add_u32_e32 v137, 0x80, v137
	s_cbranch_vccz .LBB0_389

.LBB0_404:
	s_nop 0
	v_lshl_add_u64 v[56:57], v[130:131], 1, s[10:11]
	global_load_dwordx4 v[56:59], v[56:57], off
	ds_read_b128 v[164:167], v134
	ds_read_b128 v[168:171], v134 offset:2560
	ds_read_b128 v[172:175], v135 offset:20480
	ds_read_b128 v[176:179], v135 offset:23040
	ds_read_b128 v[180:183], v134 offset:5120
	ds_read_b128 v[184:187], v134 offset:7680
	ds_read_b128 v[188:191], v135 offset:25600
	ds_read_b128 v[192:195], v135 offset:28160
	s_nop 0
	s_waitcnt lgkmcnt(5)
	v_mfma_f32_16x16x32_bf16 v[124:127], v[172:175], v[164:167], v[124:127]
	v_mfma_f32_16x16x32_bf16 v[116:119], v[172:175], v[168:171], v[116:119]
	s_waitcnt lgkmcnt(3)
	v_mfma_f32_16x16x32_bf16 v[108:111], v[172:175], v[180:183], v[108:111]
	s_waitcnt lgkmcnt(2)
	v_mfma_f32_16x16x32_bf16 v[100:103], v[172:175], v[184:187], v[100:103]
	v_mfma_f32_16x16x32_bf16 v[92:95], v[176:179], v[164:167], v[92:95]
	v_mfma_f32_16x16x32_bf16 v[84:87], v[176:179], v[168:171], v[84:87]
	s_waitcnt lgkmcnt(1)
	v_mfma_f32_16x16x32_bf16 v[120:123], v[188:191], v[164:167], v[120:123]
	v_mfma_f32_16x16x32_bf16 v[112:115], v[188:191], v[168:171], v[112:115]
	v_mfma_f32_16x16x32_bf16 v[104:107], v[188:191], v[180:183], v[104:107]
	v_mfma_f32_16x16x32_bf16 v[172:175], v[176:179], v[180:183], v[76:79]
	v_mfma_f32_16x16x32_bf16 v[176:179], v[176:179], v[184:187], v[68:71]
	v_mfma_f32_16x16x32_bf16 v[188:191], v[188:191], v[184:187], v[96:99]
	s_waitcnt lgkmcnt(0)
	v_mfma_f32_16x16x32_bf16 v[164:167], v[192:195], v[164:167], v[88:91]
	v_mfma_f32_16x16x32_bf16 v[168:171], v[192:195], v[168:171], v[80:83]
	v_mfma_f32_16x16x32_bf16 v[180:183], v[192:195], v[180:183], v[72:75]
	v_mfma_f32_16x16x32_bf16 v[184:187], v[192:195], v[184:187], v[64:67]
	s_nop 0
	ds_read_b128 v[192:195], v134 offset:64
	ds_read_b128 v[196:199], v134 offset:2624
	ds_read_b128 v[76:79], v135 offset:20544
	ds_read_b128 v[96:99], v135 offset:23104
	ds_read_b128 v[200:203], v134 offset:5184
	ds_read_b128 v[204:207], v134 offset:7744
	ds_read_b128 v[208:211], v135 offset:25664
	ds_read_b128 v[212:215], v135 offset:28224
	s_nop 0
	s_waitcnt lgkmcnt(5)
	v_mfma_f32_16x16x32_bf16 v[64:67], v[76:79], v[192:195], v[124:127]
	v_mfma_f32_16x16x32_bf16 v[68:71], v[76:79], v[196:199], v[116:119]
	s_waitcnt lgkmcnt(3)
	v_mfma_f32_16x16x32_bf16 v[72:75], v[76:79], v[200:203], v[108:111]
	s_waitcnt lgkmcnt(2)
	v_mfma_f32_16x16x32_bf16 v[76:79], v[76:79], v[204:207], v[100:103]
	v_mfma_f32_16x16x32_bf16 v[80:83], v[96:99], v[192:195], v[92:95]
	v_mfma_f32_16x16x32_bf16 v[84:87], v[96:99], v[196:199], v[84:87]
	v_mfma_f32_16x16x32_bf16 v[88:91], v[96:99], v[200:203], v[172:175]
	v_mfma_f32_16x16x32_bf16 v[92:95], v[96:99], v[204:207], v[176:179]
	s_waitcnt lgkmcnt(1)
	v_mfma_f32_16x16x32_bf16 v[96:99], v[208:211], v[192:195], v[120:123]
	v_mfma_f32_16x16x32_bf16 v[100:103], v[208:211], v[196:199], v[112:115]
	v_mfma_f32_16x16x32_bf16 v[104:107], v[208:211], v[200:203], v[104:107]
	v_mfma_f32_16x16x32_bf16 v[108:111], v[208:211], v[204:207], v[188:191]
	s_waitcnt lgkmcnt(0)
	v_mfma_f32_16x16x32_bf16 v[112:115], v[212:215], v[192:195], v[164:167]
	v_mfma_f32_16x16x32_bf16 v[116:119], v[212:215], v[196:199], v[168:171]
	v_mfma_f32_16x16x32_bf16 v[120:123], v[212:215], v[200:203], v[180:183]
	v_mfma_f32_16x16x32_bf16 v[124:127], v[212:215], v[204:207], v[184:187]
	s_nop 0
	s_cmp_gt_u32 s21, 5
	s_cselect_b64 s[6:7], -1, 0
	s_cmp_lt_u32 s21, 6
	s_cselect_b64 s[4:5], -1, 0
	s_or_b64 s[4:5], s[2:3], s[4:5]
	s_andn2_b64 vcc, exec, s[4:5]
	s_barrier
	s_cbranch_vccnz .LBB0_406
	s_waitcnt vmcnt(15)
	ds_write_b128 v145, v[4:7]
	s_waitcnt vmcnt(14)
	ds_write_b128 v145, v[12:15] offset:20480
	s_waitcnt vmcnt(13)
	ds_write_b128 v146, v[20:23]
	s_waitcnt vmcnt(12)
	ds_write_b128 v146, v[32:35] offset:20480
	s_waitcnt vmcnt(11)
	ds_write_b128 v147, v[40:43]
	s_waitcnt vmcnt(10)
	ds_write_b128 v147, v[48:51] offset:20480
	s_waitcnt vmcnt(9)
	ds_write_b128 v148, v[52:55]
	s_waitcnt vmcnt(8)
	ds_write_b128 v148, v[60:63] offset:20480

.LBB0_474:
	s_waitcnt vmcnt(15)
	v_lshl_add_u64 v[60:61], v[130:131], 1, s[8:9]
	global_load_dwordx4 v[60:63], v[60:61], off
	ds_read_b128 v[160:163], v134 offset:40960
	ds_read_b128 v[164:167], v134 offset:43520
	ds_read_b128 v[168:171], v135 offset:61440
	ds_read_b128 v[172:175], v135 offset:64000
	ds_read_b128 v[176:179], v134 offset:46080
	ds_read_b128 v[180:183], v134 offset:48640
	ds_read_b128 v[184:187], v149 offset:5120
	ds_read_b128 v[188:191], v149 offset:7680
	s_nop 0
	s_waitcnt lgkmcnt(5)
	v_mfma_f32_16x16x32_bf16 v[64:67], v[168:171], v[160:163], v[64:67]
	v_mfma_f32_16x16x32_bf16 v[68:71], v[168:171], v[164:167], v[68:71]
	s_waitcnt lgkmcnt(3)
	v_mfma_f32_16x16x32_bf16 v[72:75], v[168:171], v[176:179], v[72:75]
	s_waitcnt lgkmcnt(2)
	v_mfma_f32_16x16x32_bf16 v[76:79], v[168:171], v[180:183], v[76:79]
	v_mfma_f32_16x16x32_bf16 v[80:83], v[172:175], v[160:163], v[80:83]
	v_mfma_f32_16x16x32_bf16 v[84:87], v[172:175], v[164:167], v[84:87]
	v_mfma_f32_16x16x32_bf16 v[88:91], v[172:175], v[176:179], v[88:91]
	v_mfma_f32_16x16x32_bf16 v[92:95], v[172:175], v[180:183], v[92:95]
	s_waitcnt lgkmcnt(1)
	v_mfma_f32_16x16x32_bf16 v[168:171], v[184:187], v[160:163], v[96:99]
	v_mfma_f32_16x16x32_bf16 v[172:175], v[184:187], v[164:167], v[100:103]
	v_mfma_f32_16x16x32_bf16 v[192:195], v[184:187], v[176:179], v[104:107]
	v_mfma_f32_16x16x32_bf16 v[184:187], v[184:187], v[180:183], v[108:111]
	s_waitcnt lgkmcnt(0)
	v_mfma_f32_16x16x32_bf16 v[160:163], v[188:191], v[160:163], v[112:115]
	v_mfma_f32_16x16x32_bf16 v[164:167], v[188:191], v[164:167], v[116:119]
	v_mfma_f32_16x16x32_bf16 v[176:179], v[188:191], v[176:179], v[120:123]
	v_mfma_f32_16x16x32_bf16 v[180:183], v[188:191], v[180:183], v[124:127]
	s_nop 0
	ds_read_b128 v[188:191], v134 offset:41024
	ds_read_b128 v[196:199], v134 offset:43584
	ds_read_b128 v[96:99], v135 offset:61504
	ds_read_b128 v[200:203], v135 offset:64064
	ds_read_b128 v[204:207], v134 offset:46144
	ds_read_b128 v[208:211], v134 offset:48704
	ds_read_b128 v[212:215], v150 offset:5120
	ds_read_b128 v[216:219], v150 offset:7680
	s_nop 0
	s_waitcnt lgkmcnt(5)
	v_mfma_f32_16x16x32_bf16 v[124:127], v[96:99], v[188:191], v[64:67]
	v_mfma_f32_16x16x32_bf16 v[120:123], v[96:99], v[196:199], v[68:71]
	s_waitcnt lgkmcnt(3)
	v_mfma_f32_16x16x32_bf16 v[116:119], v[96:99], v[204:207], v[72:75]
	s_waitcnt lgkmcnt(2)
	v_mfma_f32_16x16x32_bf16 v[112:115], v[96:99], v[208:211], v[76:79]
	v_mfma_f32_16x16x32_bf16 v[108:111], v[200:203], v[188:191], v[80:83]
	v_mfma_f32_16x16x32_bf16 v[104:107], v[200:203], v[196:199], v[84:87]
	v_mfma_f32_16x16x32_bf16 v[100:103], v[200:203], v[204:207], v[88:91]
	v_mfma_f32_16x16x32_bf16 v[96:99], v[200:203], v[208:211], v[92:95]
	s_waitcnt lgkmcnt(1)
	v_mfma_f32_16x16x32_bf16 v[92:95], v[212:215], v[188:191], v[168:171]
	v_mfma_f32_16x16x32_bf16 v[88:91], v[212:215], v[196:199], v[172:175]
	v_mfma_f32_16x16x32_bf16 v[84:87], v[212:215], v[204:207], v[192:195]
	v_mfma_f32_16x16x32_bf16 v[80:83], v[212:215], v[208:211], v[184:187]
	s_waitcnt lgkmcnt(0)
	v_mfma_f32_16x16x32_bf16 v[76:79], v[216:219], v[188:191], v[160:163]
	v_mfma_f32_16x16x32_bf16 v[72:75], v[216:219], v[196:199], v[164:167]
	v_mfma_f32_16x16x32_bf16 v[68:71], v[216:219], v[204:207], v[176:179]
	v_mfma_f32_16x16x32_bf16 v[64:67], v[216:219], v[208:211], v[180:183]
	s_nop 0
	s_add_i32 s19, s19, 2
	v_add_u32_e32 v143, 0x80, v143
	v_add_u32_e32 v142, 0x80, v142
	v_add_u32_e32 v140, 0x80, v140
	s_andn2_b64 vcc, exec, s[6:7]
	v_add_u32_e32 v138, 0x80, v138
	s_cbranch_vccz .LBB0_468

.LBB0_483:
	s_nop 0
	v_lshl_add_u64 v[56:57], v[130:131], 1, s[8:9]
	global_load_dwordx4 v[56:59], v[56:57], off
	ds_read_b128 v[162:165], v134
	ds_read_b128 v[166:169], v134 offset:2560
	ds_read_b128 v[170:173], v135 offset:20480
	ds_read_b128 v[174:177], v135 offset:23040
	ds_read_b128 v[178:181], v134 offset:5120
	ds_read_b128 v[182:185], v134 offset:7680
	ds_read_b128 v[186:189], v135 offset:25600
	ds_read_b128 v[190:193], v135 offset:28160
	s_nop 0
	s_waitcnt lgkmcnt(5)
	v_mfma_f32_16x16x32_bf16 v[124:127], v[170:173], v[162:165], v[124:127]
	v_mfma_f32_16x16x32_bf16 v[120:123], v[170:173], v[166:169], v[120:123]
	s_waitcnt lgkmcnt(3)
	v_mfma_f32_16x16x32_bf16 v[116:119], v[170:173], v[178:181], v[116:119]
	s_waitcnt lgkmcnt(2)
	v_mfma_f32_16x16x32_bf16 v[112:115], v[170:173], v[182:185], v[112:115]
	v_mfma_f32_16x16x32_bf16 v[108:111], v[174:177], v[162:165], v[108:111]
	v_mfma_f32_16x16x32_bf16 v[104:107], v[174:177], v[166:169], v[104:107]
	v_mfma_f32_16x16x32_bf16 v[100:103], v[174:177], v[178:181], v[100:103]
	v_mfma_f32_16x16x32_bf16 v[96:99], v[174:177], v[182:185], v[96:99]
	s_waitcnt lgkmcnt(1)
	v_mfma_f32_16x16x32_bf16 v[170:173], v[186:189], v[162:165], v[92:95]
	v_mfma_f32_16x16x32_bf16 v[174:177], v[186:189], v[166:169], v[88:91]
	v_mfma_f32_16x16x32_bf16 v[194:197], v[186:189], v[178:181], v[84:87]
	v_mfma_f32_16x16x32_bf16 v[186:189], v[186:189], v[182:185], v[80:83]
	s_waitcnt lgkmcnt(0)
	v_mfma_f32_16x16x32_bf16 v[162:165], v[190:193], v[162:165], v[76:79]
	v_mfma_f32_16x16x32_bf16 v[166:169], v[190:193], v[166:169], v[72:75]
	v_mfma_f32_16x16x32_bf16 v[178:181], v[190:193], v[178:181], v[68:71]
	v_mfma_f32_16x16x32_bf16 v[182:185], v[190:193], v[182:185], v[64:67]
	s_nop 0
	ds_read_b128 v[190:193], v134 offset:64
	ds_read_b128 v[198:201], v134 offset:2624
	ds_read_b128 v[76:79], v135 offset:20544
	ds_read_b128 v[92:95], v135 offset:23104
	ds_read_b128 v[202:205], v134 offset:5184
	ds_read_b128 v[206:209], v134 offset:7744
	ds_read_b128 v[210:213], v135 offset:25664
	ds_read_b128 v[214:217], v135 offset:28224
	s_nop 0
	s_waitcnt lgkmcnt(5)
	v_mfma_f32_16x16x32_bf16 v[64:67], v[76:79], v[190:193], v[124:127]
	v_mfma_f32_16x16x32_bf16 v[68:71], v[76:79], v[198:201], v[120:123]
	s_waitcnt lgkmcnt(3)
	v_mfma_f32_16x16x32_bf16 v[72:75], v[76:79], v[202:205], v[116:119]
	s_waitcnt lgkmcnt(2)
	v_mfma_f32_16x16x32_bf16 v[76:79], v[76:79], v[206:209], v[112:115]
	v_mfma_f32_16x16x32_bf16 v[80:83], v[92:95], v[190:193], v[108:111]
	v_mfma_f32_16x16x32_bf16 v[84:87], v[92:95], v[198:201], v[104:107]
	v_mfma_f32_16x16x32_bf16 v[88:91], v[92:95], v[202:205], v[100:103]
	v_mfma_f32_16x16x32_bf16 v[92:95], v[92:95], v[206:209], v[96:99]
	s_waitcnt lgkmcnt(1)
	v_mfma_f32_16x16x32_bf16 v[96:99], v[210:213], v[190:193], v[170:173]
	v_mfma_f32_16x16x32_bf16 v[100:103], v[210:213], v[198:201], v[174:177]
	v_mfma_f32_16x16x32_bf16 v[104:107], v[210:213], v[202:205], v[194:197]
	v_mfma_f32_16x16x32_bf16 v[108:111], v[210:213], v[206:209], v[186:189]
	s_waitcnt lgkmcnt(0)
	v_mfma_f32_16x16x32_bf16 v[112:115], v[214:217], v[190:193], v[162:165]
	v_mfma_f32_16x16x32_bf16 v[116:119], v[214:217], v[198:201], v[166:169]
	v_mfma_f32_16x16x32_bf16 v[120:123], v[214:217], v[202:205], v[178:181]
	v_mfma_f32_16x16x32_bf16 v[124:127], v[214:217], v[206:209], v[182:185]
	s_nop 0
	s_cmp_gt_u32 s19, 13
	s_cselect_b64 s[6:7], -1, 0
	s_cmp_lt_u32 s19, 14
	s_cselect_b64 s[4:5], -1, 0
	s_or_b64 s[4:5], s[2:3], s[4:5]
	s_andn2_b64 vcc, exec, s[4:5]
	s_barrier
	s_cbranch_vccnz .LBB0_485
	s_waitcnt vmcnt(15)
	ds_write_b128 v144, v[4:7]
	s_waitcnt vmcnt(14)
	ds_write_b128 v144, v[12:15] offset:20480
	s_waitcnt vmcnt(13)
	ds_write_b128 v145, v[20:23]
	s_waitcnt vmcnt(12)
	ds_write_b128 v145, v[32:35] offset:20480
	s_waitcnt vmcnt(11)
	ds_write_b128 v146, v[40:43]
	s_waitcnt vmcnt(10)
	ds_write_b128 v146, v[48:51] offset:20480
	s_waitcnt vmcnt(9)
	ds_write_b128 v147, v[52:55]
	s_waitcnt vmcnt(8)
	ds_write_b128 v147, v[60:63] offset:20480

.LBB0_704:
	s_waitcnt vmcnt(15)
	v_lshl_add_u64 v[60:61], v[130:131], 1, s[12:13]
	global_load_dwordx4 v[60:63], v[60:61], off
	ds_read_b128 v[184:187], v136 offset:40960
	ds_read_b128 v[188:191], v136 offset:43520
	ds_read_b128 v[192:195], v137 offset:61440
	ds_read_b128 v[196:199], v137 offset:64000
	ds_read_b128 v[200:203], v136 offset:46080
	ds_read_b128 v[204:207], v136 offset:48640
	ds_read_b128 v[208:211], v161
	ds_read_b128 v[212:215], v162
	s_nop 0
	s_waitcnt lgkmcnt(5)
	v_mfma_f32_16x16x32_bf16 v[64:67], v[192:195], v[184:187], v[64:67]
	v_mfma_f32_16x16x32_bf16 v[68:71], v[192:195], v[188:191], v[68:71]
	s_waitcnt lgkmcnt(3)
	v_mfma_f32_16x16x32_bf16 v[72:75], v[192:195], v[200:203], v[72:75]
	s_waitcnt lgkmcnt(2)
	v_mfma_f32_16x16x32_bf16 v[76:79], v[192:195], v[204:207], v[76:79]
	v_mfma_f32_16x16x32_bf16 v[80:83], v[196:199], v[184:187], v[80:83]
	v_mfma_f32_16x16x32_bf16 v[84:87], v[196:199], v[188:191], v[84:87]
	v_mfma_f32_16x16x32_bf16 v[88:91], v[196:199], v[200:203], v[88:91]
	s_waitcnt lgkmcnt(1)
	v_mfma_f32_16x16x32_bf16 v[96:99], v[208:211], v[184:187], v[96:99]
	s_waitcnt lgkmcnt(0)
	v_mfma_f32_16x16x32_bf16 v[112:115], v[212:215], v[184:187], v[112:115]
	v_mfma_f32_16x16x32_bf16 v[192:195], v[196:199], v[204:207], v[92:95]
	v_mfma_f32_16x16x32_bf16 v[196:199], v[208:211], v[188:191], v[100:103]
	v_mfma_f32_16x16x32_bf16 v[216:219], v[208:211], v[200:203], v[104:107]
	v_mfma_f32_16x16x32_bf16 v[208:211], v[208:211], v[204:207], v[108:111]
	v_mfma_f32_16x16x32_bf16 v[184:187], v[212:215], v[188:191], v[116:119]
	v_mfma_f32_16x16x32_bf16 v[188:191], v[212:215], v[200:203], v[120:123]
	v_mfma_f32_16x16x32_bf16 v[200:203], v[212:215], v[204:207], v[124:127]
	s_nop 0
	ds_read_b128 v[204:207], v136 offset:41024
	ds_read_b128 v[212:215], v136 offset:43584
	ds_read_b128 v[100:103], v137 offset:61504
	ds_read_b128 v[104:107], v137 offset:64064
	ds_read_b128 v[220:223], v136 offset:46144
	ds_read_b128 v[224:227], v136 offset:48704
	ds_read_b128 v[228:231], v163
	ds_read_b128 v[232:235], v164
	s_nop 0
	s_waitcnt lgkmcnt(5)
	v_mfma_f32_16x16x32_bf16 v[124:127], v[100:103], v[204:207], v[64:67]
	v_mfma_f32_16x16x32_bf16 v[108:111], v[100:103], v[212:215], v[68:71]
	s_waitcnt lgkmcnt(3)
	v_mfma_f32_16x16x32_bf16 v[92:95], v[100:103], v[220:223], v[72:75]
	s_waitcnt lgkmcnt(2)
	v_mfma_f32_16x16x32_bf16 v[76:79], v[100:103], v[224:227], v[76:79]
	v_mfma_f32_16x16x32_bf16 v[116:119], v[104:107], v[204:207], v[80:83]
	v_mfma_f32_16x16x32_bf16 v[100:103], v[104:107], v[212:215], v[84:87]
	v_mfma_f32_16x16x32_bf16 v[84:87], v[104:107], v[220:223], v[88:91]
	v_mfma_f32_16x16x32_bf16 v[68:71], v[104:107], v[224:227], v[192:195]
	s_waitcnt lgkmcnt(1)
	v_mfma_f32_16x16x32_bf16 v[120:123], v[228:231], v[204:207], v[96:99]
	v_mfma_f32_16x16x32_bf16 v[104:107], v[228:231], v[212:215], v[196:199]
	v_mfma_f32_16x16x32_bf16 v[88:91], v[228:231], v[220:223], v[216:219]
	v_mfma_f32_16x16x32_bf16 v[72:75], v[228:231], v[224:227], v[208:211]
	s_waitcnt lgkmcnt(0)
	v_mfma_f32_16x16x32_bf16 v[112:115], v[232:235], v[204:207], v[112:115]
	v_mfma_f32_16x16x32_bf16 v[96:99], v[232:235], v[212:215], v[184:187]
	v_mfma_f32_16x16x32_bf16 v[80:83], v[232:235], v[220:223], v[188:191]
	v_mfma_f32_16x16x32_bf16 v[64:67], v[232:235], v[224:227], v[200:203]
	s_nop 0
	s_add_i32 s2, s2, 2
	v_add_u32_e32 v182, 0x80, v182
	v_add_u32_e32 v181, 0x80, v181
	v_add_u32_e32 v180, 0x80, v180
	v_add_u32_e32 v179, 0x80, v179
	v_add_u32_e32 v178, 0x80, v178
	v_add_u32_e32 v177, 0x80, v177
	v_add_u32_e32 v176, 0x80, v176
	v_add_u32_e32 v175, 0x80, v175
	v_add_u32_e32 v174, 0x80, v174
	v_add_u32_e32 v173, 0x80, v173
	s_and_b64 vcc, exec, s[0:1]
	s_cbranch_vccnz .LBB0_723

.LBB0_713:
	s_nop 0
	v_lshl_add_u64 v[56:57], v[130:131], 1, s[12:13]
	global_load_dwordx4 v[56:59], v[56:57], off
	ds_read_b128 v[184:187], v136
	ds_read_b128 v[188:191], v136 offset:2560
	ds_read_b128 v[192:195], v137 offset:20480
	ds_read_b128 v[196:199], v137 offset:23040
	ds_read_b128 v[200:203], v136 offset:5120
	ds_read_b128 v[204:207], v136 offset:7680
	ds_read_b128 v[208:211], v137 offset:25600
	ds_read_b128 v[212:215], v137 offset:28160
	s_nop 0
	s_waitcnt lgkmcnt(5)
	v_mfma_f32_16x16x32_bf16 v[124:127], v[192:195], v[184:187], v[124:127]
	v_mfma_f32_16x16x32_bf16 v[108:111], v[192:195], v[188:191], v[108:111]
	s_waitcnt lgkmcnt(3)
	v_mfma_f32_16x16x32_bf16 v[92:95], v[192:195], v[200:203], v[92:95]
	s_waitcnt lgkmcnt(2)
	v_mfma_f32_16x16x32_bf16 v[76:79], v[192:195], v[204:207], v[76:79]
	v_mfma_f32_16x16x32_bf16 v[116:119], v[196:199], v[184:187], v[116:119]
	v_mfma_f32_16x16x32_bf16 v[100:103], v[196:199], v[188:191], v[100:103]
	s_waitcnt lgkmcnt(1)
	v_mfma_f32_16x16x32_bf16 v[120:123], v[208:211], v[184:187], v[120:123]
	v_mfma_f32_16x16x32_bf16 v[104:107], v[208:211], v[188:191], v[104:107]
	s_waitcnt lgkmcnt(0)
	v_mfma_f32_16x16x32_bf16 v[112:115], v[212:215], v[184:187], v[112:115]
	v_mfma_f32_16x16x32_bf16 v[192:195], v[196:199], v[200:203], v[84:87]
	v_mfma_f32_16x16x32_bf16 v[196:199], v[196:199], v[204:207], v[68:71]
	v_mfma_f32_16x16x32_bf16 v[216:219], v[208:211], v[200:203], v[88:91]
	v_mfma_f32_16x16x32_bf16 v[208:211], v[208:211], v[204:207], v[72:75]
	v_mfma_f32_16x16x32_bf16 v[184:187], v[212:215], v[188:191], v[96:99]
	v_mfma_f32_16x16x32_bf16 v[188:191], v[212:215], v[200:203], v[80:83]
	v_mfma_f32_16x16x32_bf16 v[200:203], v[212:215], v[204:207], v[64:67]
	s_nop 0
	ds_read_b128 v[204:207], v136 offset:64
	ds_read_b128 v[212:215], v136 offset:2624
	ds_read_b128 v[80:83], v137 offset:20544
	ds_read_b128 v[96:99], v137 offset:23104
	ds_read_b128 v[220:223], v136 offset:5184
	ds_read_b128 v[224:227], v136 offset:7744
	ds_read_b128 v[228:231], v137 offset:25664
	ds_read_b128 v[232:235], v137 offset:28224
	s_nop 0
	s_waitcnt lgkmcnt(5)
	v_mfma_f32_16x16x32_bf16 v[64:67], v[80:83], v[204:207], v[124:127]
	v_mfma_f32_16x16x32_bf16 v[68:71], v[80:83], v[212:215], v[108:111]
	s_waitcnt lgkmcnt(3)
	v_mfma_f32_16x16x32_bf16 v[72:75], v[80:83], v[220:223], v[92:95]
	s_waitcnt lgkmcnt(2)
	v_mfma_f32_16x16x32_bf16 v[76:79], v[80:83], v[224:227], v[76:79]
	v_mfma_f32_16x16x32_bf16 v[80:83], v[96:99], v[204:207], v[116:119]
	v_mfma_f32_16x16x32_bf16 v[84:87], v[96:99], v[212:215], v[100:103]
	v_mfma_f32_16x16x32_bf16 v[88:91], v[96:99], v[220:223], v[192:195]
	v_mfma_f32_16x16x32_bf16 v[92:95], v[96:99], v[224:227], v[196:199]
	s_waitcnt lgkmcnt(1)
	v_mfma_f32_16x16x32_bf16 v[96:99], v[228:231], v[204:207], v[120:123]
	v_mfma_f32_16x16x32_bf16 v[100:103], v[228:231], v[212:215], v[104:107]
	v_mfma_f32_16x16x32_bf16 v[104:107], v[228:231], v[220:223], v[216:219]
	v_mfma_f32_16x16x32_bf16 v[108:111], v[228:231], v[224:227], v[208:211]
	s_waitcnt lgkmcnt(0)
	v_mfma_f32_16x16x32_bf16 v[112:115], v[232:235], v[204:207], v[112:115]
	v_mfma_f32_16x16x32_bf16 v[116:119], v[232:235], v[212:215], v[184:187]
	v_mfma_f32_16x16x32_bf16 v[120:123], v[232:235], v[220:223], v[188:191]
	v_mfma_f32_16x16x32_bf16 v[124:127], v[232:235], v[224:227], v[200:203]
	s_nop 0
	s_cmp_gt_u32 s2, 13
	s_cselect_b64 s[0:1], -1, 0
	s_cmp_lt_u32 s2, 14
	s_cselect_b64 s[4:5], -1, 0
	s_or_b64 s[4:5], s[10:11], s[4:5]
	s_andn2_b64 vcc, exec, s[4:5]
	s_barrier
	s_cbranch_vccnz .LBB0_715
	s_waitcnt vmcnt(15)
	ds_write_b128 v141, v[4:7]
	s_waitcnt vmcnt(14)
	ds_write_b128 v141, v[12:15] offset:20480
	s_waitcnt vmcnt(13)
	ds_write_b128 v158, v[20:23]
	s_waitcnt vmcnt(12)
	ds_write_b128 v158, v[32:35] offset:20480
	s_waitcnt vmcnt(11)
	ds_write_b128 v159, v[40:43]
	s_waitcnt vmcnt(10)
	ds_write_b128 v159, v[48:51] offset:20480
	s_waitcnt vmcnt(9)
	ds_write_b128 v160, v[52:55]
	s_waitcnt vmcnt(8)
	ds_write_b128 v160, v[60:63] offset:20480

.LBB0_843:
	v_lshlrev_b32_e32 v65, 1, v136
	v_lshl_add_u32 v155, v74, 1, v65
	v_lshl_add_u32 v156, v71, 1, v65
	v_lshl_add_u32 v157, v72, 1, v65
	v_lshl_add_u32 v158, v73, 1, v65
	v_or_b32_e32 v65, 0xc0, v136
	s_waitcnt lgkmcnt(0)
	s_barrier
	s_waitcnt vmcnt(15)
	ds_write_b128 v155, v[0:3] offset:40960
	s_waitcnt vmcnt(14)
	ds_write_b128 v155, v[8:11] offset:61440
	s_waitcnt vmcnt(13)
	ds_write_b128 v156, v[16:19] offset:40960
	s_waitcnt vmcnt(12)
	ds_write_b128 v156, v[24:27] offset:61440
	s_waitcnt vmcnt(11)
	ds_write_b128 v157, v[28:31] offset:40960
	s_waitcnt vmcnt(10)
	ds_write_b128 v157, v[36:39] offset:61440
	s_waitcnt vmcnt(9)
	ds_write_b128 v158, v[44:47] offset:40960
	s_waitcnt vmcnt(8)
	ds_write_b128 v158, v[56:59] offset:61440
	v_add_u32_e32 v44, v65, v142
	v_mov_b32_e32 v132, v44
	v_mul_lo_u32 v66, v146, s6
	v_lshl_add_u64 v[0:1], v[132:133], 1, s[88:89]
	v_add_u32_e32 v132, v65, v144
	global_load_dwordx4 v[0:3], v[0:1], off
	v_bfe_u32 v66, v66, 10, 6
	v_lshl_add_u64 v[8:9], v[132:133], 1, s[18:19]
	v_add_u32_e32 v132, 0x4000, v44
	global_load_dwordx4 v[8:11], v[8:9], off
	v_mul_lo_u32 v67, v66, -6
	v_lshl_add_u64 v[16:17], v[132:133], 1, s[88:89]
	v_add_u32_e32 v132, v65, v137
	global_load_dwordx4 v[16:19], v[16:17], off
	v_add_u32_e32 v151, v67, v146
	v_lshl_add_u64 v[24:25], v[132:133], 1, s[18:19]
	v_add_u32_e32 v132, 0x8000, v44
	global_load_dwordx4 v[24:27], v[24:25], off
	v_cmp_gt_i32_e32 vcc, 5, v151
	v_lshl_add_u64 v[28:29], v[132:133], 1, s[88:89]
	v_add_u32_e32 v132, v65, v148
	global_load_dwordx4 v[28:31], v[28:29], off
	v_cndmask_b32_e64 v67, 2, 1, vcc
	v_lshl_add_u64 v[36:37], v[132:133], 1, s[18:19]
	v_add_u32_e32 v132, 0xc000, v44
	global_load_dwordx4 v[36:39], v[36:37], off
	v_cmp_gt_i32_e64 s[12:13], 3, v151
	v_lshl_add_u64 v[44:45], v[132:133], 1, s[88:89]
	v_add_u32_e32 v132, v65, v149
	global_load_dwordx4 v[44:47], v[44:45], off
	v_cndmask_b32_e64 v152, v67, 0, s[12:13]
	v_lshl_add_u64 v[56:57], v[132:133], 1, s[18:19]
	global_load_dwordx4 v[56:59], v[56:57], off
	v_add_u32_e32 v64, v64, v145
	v_add_lshl_u32 v150, v64, v140, 9
	s_lshl_b32 s0, s33, 15
	v_lshlrev_b32_e32 v64, 20, v66
	v_lshlrev_b32_e32 v66, 18, v152
	s_and_b32 s0, s0, 0x38000
	v_or_b32_e32 v64, v66, v64
	v_or_b32_e32 v64, s0, v64
	v_add_u32_e32 v153, v64, v141
	v_and_b32_e32 v64, 15, v131
	v_bfe_u32 v159, v131, 4, 2
	v_ashrrev_i32_e32 v66, 1, v131
	s_movk_i32 s0, 0xffc0
	v_and_or_b32 v154, v66, s0, v64
	v_lshlrev_b32_e32 v64, 4, v159
	v_and_b32_e32 v66, 0x4f, v131
	s_movk_i32 s0, 0xa0
	v_mad_u64_u32 v[134:135], s[0:1], v154, s0, v[64:65]
	v_mul_u32_u24_e32 v66, 0x50, v66
	v_lshl_add_u32 v135, v66, 1, v64
	v_add_u32_e32 v64, v144, v143
	v_add_u32_e32 v164, v65, v64
	v_add_u32_e32 v166, v136, v64
	ds_read_b128 v[64:67], v134
	ds_read_b128 v[68:71], v134 offset:2560
	ds_read_b128 v[72:75], v135 offset:20480
	ds_read_b128 v[76:79], v135 offset:23040
	ds_read_b128 v[80:83], v134 offset:5120
	ds_read_b128 v[84:87], v134 offset:7680
	ds_read_b128 v[88:91], v135 offset:25600
	ds_read_b128 v[92:95], v135 offset:28160
	v_add_u32_e32 v162, v142, v136
	s_mov_b32 s2, 2
	s_mov_b32 s14, 0
	v_add_u32_e32 v160, 0xf000, v135
	v_add_u32_e32 v161, 0xf040, v135
	v_add_u32_e32 v163, 0x1c0, v162
	v_add_u32_e32 v165, 0x41c0, v162
	v_add_u32_e32 v167, 0x20c0, v166
	v_add_u32_e32 v168, 0x81c0, v162
	v_add_u32_e32 v169, 0x40c0, v166
	v_add_u32_e32 v170, 0xc1c0, v162
	v_add_u32_e32 v171, 0x60c0, v166
	v_add_u32_e32 v172, 0x2000, v153
	v_add_u32_e32 v173, 0x4000, v153
	v_add_u32_e32 v174, 0x6000, v153
	s_nop 0
	s_waitcnt lgkmcnt(5)
	v_mfma_f32_16x16x32_bf16 v[96:99], v[72:75], v[64:67], 0
	v_mfma_f32_16x16x32_bf16 v[100:103], v[72:75], v[68:71], 0
	s_waitcnt lgkmcnt(3)
	v_mfma_f32_16x16x32_bf16 v[104:107], v[72:75], v[80:83], 0
	s_waitcnt lgkmcnt(2)
	v_mfma_f32_16x16x32_bf16 v[72:75], v[72:75], v[84:87], 0
	v_mfma_f32_16x16x32_bf16 v[108:111], v[76:79], v[64:67], 0
	v_mfma_f32_16x16x32_bf16 v[112:115], v[76:79], v[68:71], 0
	v_mfma_f32_16x16x32_bf16 v[116:119], v[76:79], v[80:83], 0
	v_mfma_f32_16x16x32_bf16 v[76:79], v[76:79], v[84:87], 0
	s_waitcnt lgkmcnt(1)
	v_mfma_f32_16x16x32_bf16 v[120:123], v[88:91], v[64:67], 0
	v_mfma_f32_16x16x32_bf16 v[124:127], v[88:91], v[68:71], 0
	v_mfma_f32_16x16x32_bf16 v[176:179], v[88:91], v[80:83], 0
	v_mfma_f32_16x16x32_bf16 v[88:91], v[88:91], v[84:87], 0
	s_waitcnt lgkmcnt(0)
	v_mfma_f32_16x16x32_bf16 v[64:67], v[92:95], v[64:67], 0
	v_mfma_f32_16x16x32_bf16 v[68:71], v[92:95], v[68:71], 0
	v_mfma_f32_16x16x32_bf16 v[80:83], v[92:95], v[80:83], 0
	v_mfma_f32_16x16x32_bf16 v[84:87], v[92:95], v[84:87], 0
	s_nop 0
	ds_read_b128 v[92:95], v134 offset:64
	ds_read_b128 v[180:183], v134 offset:2624
	ds_read_b128 v[184:187], v135 offset:20544
	ds_read_b128 v[188:191], v135 offset:23104
	ds_read_b128 v[192:195], v134 offset:5184
	ds_read_b128 v[196:199], v134 offset:7744
	ds_read_b128 v[200:203], v135 offset:25664
	ds_read_b128 v[204:207], v135 offset:28224
	s_nop 0
	s_waitcnt lgkmcnt(5)
	v_mfma_f32_16x16x32_bf16 v[96:99], v[184:187], v[92:95], v[96:99]
	v_mfma_f32_16x16x32_bf16 v[100:103], v[184:187], v[180:183], v[100:103]
	s_waitcnt lgkmcnt(3)
	v_mfma_f32_16x16x32_bf16 v[104:107], v[184:187], v[192:195], v[104:107]
	s_waitcnt lgkmcnt(2)
	v_mfma_f32_16x16x32_bf16 v[72:75], v[184:187], v[196:199], v[72:75]
	v_mfma_f32_16x16x32_bf16 v[108:111], v[188:191], v[92:95], v[108:111]
	v_mfma_f32_16x16x32_bf16 v[112:115], v[188:191], v[180:183], v[112:115]
	v_mfma_f32_16x16x32_bf16 v[116:119], v[188:191], v[192:195], v[116:119]
	v_mfma_f32_16x16x32_bf16 v[76:79], v[188:191], v[196:199], v[76:79]
	s_waitcnt lgkmcnt(1)
	v_mfma_f32_16x16x32_bf16 v[120:123], v[200:203], v[92:95], v[120:123]
	v_mfma_f32_16x16x32_bf16 v[124:127], v[200:203], v[180:183], v[124:127]
	v_mfma_f32_16x16x32_bf16 v[88:91], v[200:203], v[196:199], v[88:91]
	s_waitcnt lgkmcnt(0)
	v_mfma_f32_16x16x32_bf16 v[64:67], v[204:207], v[92:95], v[64:67]
	v_mfma_f32_16x16x32_bf16 v[68:71], v[204:207], v[180:183], v[68:71]
	v_mfma_f32_16x16x32_bf16 v[80:83], v[204:207], v[192:195], v[80:83]
	v_mfma_f32_16x16x32_bf16 v[84:87], v[204:207], v[196:199], v[84:87]
	v_mfma_f32_16x16x32_bf16 v[176:179], v[200:203], v[192:195], v[176:179]
	s_nop 0
	v_add_u32_e32 v132, 0x100, v162
	s_barrier
	s_waitcnt vmcnt(15)
	ds_write_b128 v155, v[4:7]
	s_waitcnt vmcnt(14)
	ds_write_b128 v155, v[12:15] offset:20480
	s_waitcnt vmcnt(13)
	ds_write_b128 v156, v[20:23]
	s_waitcnt vmcnt(12)
	ds_write_b128 v156, v[32:35] offset:20480
	s_waitcnt vmcnt(11)
	ds_write_b128 v157, v[40:43]
	s_waitcnt vmcnt(10)
	ds_write_b128 v157, v[48:51] offset:20480
	s_waitcnt vmcnt(9)
	ds_write_b128 v158, v[52:55]
	s_waitcnt vmcnt(8)
	ds_write_b128 v158, v[60:63] offset:20480
	s_nop 0
	v_lshl_add_u64 v[4:5], v[132:133], 1, s[88:89]
	v_mov_b32_e32 v132, v166
	global_load_dwordx4 v[4:7], v[4:5], off
	s_nop 0
	v_lshl_add_u64 v[12:13], v[132:133], 1, s[18:19]
	v_add_u32_e32 v132, 0x4100, v162
	global_load_dwordx4 v[12:15], v[12:13], off
	s_nop 0
	v_lshl_add_u64 v[20:21], v[132:133], 1, s[88:89]
	v_add_u32_e32 v132, 0x2000, v166
	global_load_dwordx4 v[20:23], v[20:21], off
	s_nop 0
	v_lshl_add_u64 v[32:33], v[132:133], 1, s[18:19]
	v_add_u32_e32 v132, 0x8100, v162
	global_load_dwordx4 v[32:35], v[32:33], off
	s_nop 0
	v_lshl_add_u64 v[40:41], v[132:133], 1, s[88:89]
	v_add_u32_e32 v132, 0x4000, v166
	global_load_dwordx4 v[40:43], v[40:41], off
	s_nop 0
	v_lshl_add_u64 v[48:49], v[132:133], 1, s[18:19]
	v_add_u32_e32 v132, 0xc100, v162
	global_load_dwordx4 v[48:51], v[48:49], off
	s_nop 0
	v_lshl_add_u64 v[52:53], v[132:133], 1, s[88:89]
	v_add_u32_e32 v132, 0x6000, v166
	global_load_dwordx4 v[52:55], v[52:53], off
	s_nop 0
	v_lshl_add_u64 v[60:61], v[132:133], 1, s[18:19]
	global_load_dwordx4 v[60:63], v[60:61], off
	ds_read_b128 v[92:95], v134 offset:40960
	ds_read_b128 v[180:183], v134 offset:43520
	ds_read_b128 v[184:187], v135 offset:61440
	ds_read_b128 v[188:191], v135 offset:64000
	ds_read_b128 v[192:195], v134 offset:46080
	ds_read_b128 v[196:199], v134 offset:48640
	ds_read_b128 v[200:203], v160 offset:5120
	ds_read_b128 v[204:207], v160 offset:7680
	s_nop 0
	s_waitcnt lgkmcnt(5)
	v_mfma_f32_16x16x32_bf16 v[96:99], v[184:187], v[92:95], v[96:99]
	v_mfma_f32_16x16x32_bf16 v[100:103], v[184:187], v[180:183], v[100:103]
	s_waitcnt lgkmcnt(3)
	v_mfma_f32_16x16x32_bf16 v[104:107], v[184:187], v[192:195], v[104:107]
	s_waitcnt lgkmcnt(2)
	v_mfma_f32_16x16x32_bf16 v[72:75], v[184:187], v[196:199], v[72:75]
	v_mfma_f32_16x16x32_bf16 v[112:115], v[188:191], v[180:183], v[112:115]
	v_mfma_f32_16x16x32_bf16 v[116:119], v[188:191], v[192:195], v[116:119]
	s_waitcnt lgkmcnt(0)
	v_mfma_f32_16x16x32_bf16 v[64:67], v[204:207], v[92:95], v[64:67]
	v_mfma_f32_16x16x32_bf16 v[80:83], v[204:207], v[192:195], v[80:83]
	v_mfma_f32_16x16x32_bf16 v[184:187], v[188:191], v[92:95], v[108:111]
	v_mfma_f32_16x16x32_bf16 v[188:191], v[188:191], v[196:199], v[76:79]
	v_mfma_f32_16x16x32_bf16 v[208:211], v[200:203], v[92:95], v[120:123]
	v_mfma_f32_16x16x32_bf16 v[212:215], v[200:203], v[180:183], v[124:127]
	v_mfma_f32_16x16x32_bf16 v[176:179], v[200:203], v[192:195], v[176:179]
	v_mfma_f32_16x16x32_bf16 v[200:203], v[200:203], v[196:199], v[88:91]
	v_mfma_f32_16x16x32_bf16 v[180:183], v[204:207], v[180:183], v[68:71]
	v_mfma_f32_16x16x32_bf16 v[192:195], v[204:207], v[196:199], v[84:87]
	s_nop 0
	ds_read_b128 v[196:199], v134 offset:41024
	ds_read_b128 v[204:207], v134 offset:43584
	ds_read_b128 v[68:71], v135 offset:61504
	ds_read_b128 v[84:87], v135 offset:64064
	ds_read_b128 v[216:219], v134 offset:46144
	ds_read_b128 v[220:223], v134 offset:48704
	ds_read_b128 v[224:227], v161 offset:5120
	ds_read_b128 v[228:231], v161 offset:7680
	s_nop 0
	s_waitcnt lgkmcnt(5)
	v_mfma_f32_16x16x32_bf16 v[124:127], v[68:71], v[196:199], v[96:99]
	v_mfma_f32_16x16x32_bf16 v[108:111], v[68:71], v[204:207], v[100:103]
	s_waitcnt lgkmcnt(3)
	v_mfma_f32_16x16x32_bf16 v[92:95], v[68:71], v[216:219], v[104:107]
	s_waitcnt lgkmcnt(2)
	v_mfma_f32_16x16x32_bf16 v[76:79], v[68:71], v[220:223], v[72:75]
	v_mfma_f32_16x16x32_bf16 v[120:123], v[84:87], v[196:199], v[184:187]
	v_mfma_f32_16x16x32_bf16 v[104:107], v[84:87], v[204:207], v[112:115]
	v_mfma_f32_16x16x32_bf16 v[88:91], v[84:87], v[216:219], v[116:119]
	v_mfma_f32_16x16x32_bf16 v[72:75], v[84:87], v[220:223], v[188:191]
	s_waitcnt lgkmcnt(1)
	v_mfma_f32_16x16x32_bf16 v[116:119], v[224:227], v[196:199], v[208:211]
	v_mfma_f32_16x16x32_bf16 v[100:103], v[224:227], v[204:207], v[212:215]
	v_mfma_f32_16x16x32_bf16 v[84:87], v[224:227], v[216:219], v[176:179]
	v_mfma_f32_16x16x32_bf16 v[68:71], v[224:227], v[220:223], v[200:203]
	s_waitcnt lgkmcnt(0)
	v_mfma_f32_16x16x32_bf16 v[112:115], v[228:231], v[196:199], v[64:67]
	v_mfma_f32_16x16x32_bf16 v[96:99], v[228:231], v[204:207], v[180:183]
	v_mfma_f32_16x16x32_bf16 v[80:83], v[228:231], v[216:219], v[80:83]
	v_mfma_f32_16x16x32_bf16 v[64:67], v[228:231], v[220:223], v[192:195]
	s_nop 0
	v_add_u32_e32 v175, v150, v136
	s_branch .LBB0_845
.LBB0_844:
	s_waitcnt vmcnt(15)
	v_lshl_add_u64 v[60:61], v[132:133], 1, s[18:19]
	global_load_dwordx4 v[60:63], v[60:61], off
	ds_read_b128 v[176:179], v134 offset:40960
	ds_read_b128 v[180:183], v134 offset:43520
	ds_read_b128 v[184:187], v135 offset:61440
	ds_read_b128 v[188:191], v135 offset:64000
	ds_read_b128 v[192:195], v134 offset:46080
	ds_read_b128 v[196:199], v134 offset:48640
	ds_read_b128 v[200:203], v160 offset:5120
	ds_read_b128 v[204:207], v160 offset:7680
	s_nop 0
	s_waitcnt lgkmcnt(5)
	v_mfma_f32_16x16x32_bf16 v[64:67], v[184:187], v[176:179], v[64:67]
	v_mfma_f32_16x16x32_bf16 v[68:71], v[184:187], v[180:183], v[68:71]
	s_waitcnt lgkmcnt(3)
	v_mfma_f32_16x16x32_bf16 v[72:75], v[184:187], v[192:195], v[72:75]
	s_waitcnt lgkmcnt(2)
	v_mfma_f32_16x16x32_bf16 v[76:79], v[184:187], v[196:199], v[76:79]
	v_mfma_f32_16x16x32_bf16 v[80:83], v[188:191], v[176:179], v[80:83]
	v_mfma_f32_16x16x32_bf16 v[84:87], v[188:191], v[180:183], v[84:87]
	v_mfma_f32_16x16x32_bf16 v[88:91], v[188:191], v[192:195], v[88:91]
	s_waitcnt lgkmcnt(1)
	v_mfma_f32_16x16x32_bf16 v[96:99], v[200:203], v[176:179], v[96:99]
	v_mfma_f32_16x16x32_bf16 v[100:103], v[200:203], v[180:183], v[100:103]
	s_waitcnt lgkmcnt(0)
	v_mfma_f32_16x16x32_bf16 v[112:115], v[204:207], v[176:179], v[112:115]
	v_mfma_f32_16x16x32_bf16 v[184:187], v[188:191], v[196:199], v[92:95]
	v_mfma_f32_16x16x32_bf16 v[188:191], v[200:203], v[192:195], v[104:107]
	v_mfma_f32_16x16x32_bf16 v[200:203], v[200:203], v[196:199], v[108:111]
	v_mfma_f32_16x16x32_bf16 v[176:179], v[204:207], v[180:183], v[116:119]
	v_mfma_f32_16x16x32_bf16 v[180:183], v[204:207], v[192:195], v[120:123]
	v_mfma_f32_16x16x32_bf16 v[192:195], v[204:207], v[196:199], v[124:127]
	s_nop 0
	ds_read_b128 v[196:199], v134 offset:41024
	ds_read_b128 v[204:207], v134 offset:43584
	ds_read_b128 v[104:107], v135 offset:61504
	ds_read_b128 v[116:119], v135 offset:64064
	ds_read_b128 v[208:211], v134 offset:46144
	ds_read_b128 v[212:215], v134 offset:48704
	ds_read_b128 v[216:219], v161 offset:5120
	ds_read_b128 v[220:223], v161 offset:7680
	s_nop 0
	s_waitcnt lgkmcnt(5)
	v_mfma_f32_16x16x32_bf16 v[124:127], v[104:107], v[196:199], v[64:67]
	v_mfma_f32_16x16x32_bf16 v[108:111], v[104:107], v[204:207], v[68:71]
	s_waitcnt lgkmcnt(3)
	v_mfma_f32_16x16x32_bf16 v[92:95], v[104:107], v[208:211], v[72:75]
	s_waitcnt lgkmcnt(2)
	v_mfma_f32_16x16x32_bf16 v[76:79], v[104:107], v[212:215], v[76:79]
	v_mfma_f32_16x16x32_bf16 v[120:123], v[116:119], v[196:199], v[80:83]
	v_mfma_f32_16x16x32_bf16 v[104:107], v[116:119], v[204:207], v[84:87]
	v_mfma_f32_16x16x32_bf16 v[88:91], v[116:119], v[208:211], v[88:91]
	v_mfma_f32_16x16x32_bf16 v[72:75], v[116:119], v[212:215], v[184:187]
	s_waitcnt lgkmcnt(1)
	v_mfma_f32_16x16x32_bf16 v[116:119], v[216:219], v[196:199], v[96:99]
	v_mfma_f32_16x16x32_bf16 v[100:103], v[216:219], v[204:207], v[100:103]
	v_mfma_f32_16x16x32_bf16 v[84:87], v[216:219], v[208:211], v[188:191]
	v_mfma_f32_16x16x32_bf16 v[68:71], v[216:219], v[212:215], v[200:203]
	s_waitcnt lgkmcnt(0)
	v_mfma_f32_16x16x32_bf16 v[112:115], v[220:223], v[196:199], v[112:115]
	v_mfma_f32_16x16x32_bf16 v[96:99], v[220:223], v[204:207], v[176:179]
	v_mfma_f32_16x16x32_bf16 v[80:83], v[220:223], v[208:211], v[180:183]
	v_mfma_f32_16x16x32_bf16 v[64:67], v[220:223], v[212:215], v[192:195]
	s_nop 0
	s_add_i32 s2, s2, 2
	s_addk_i32 s14, 0x80
	s_and_b64 vcc, exec, s[0:1]
	s_cbranch_vccnz .LBB0_863

.LBB0_853:
	s_nop 0
	v_lshl_add_u64 v[56:57], v[132:133], 1, s[18:19]
	global_load_dwordx4 v[56:59], v[56:57], off
	ds_read_b128 v[178:181], v134
	ds_read_b128 v[182:185], v134 offset:2560
	ds_read_b128 v[186:189], v135 offset:20480
	ds_read_b128 v[190:193], v135 offset:23040
	ds_read_b128 v[194:197], v134 offset:5120
	ds_read_b128 v[198:201], v134 offset:7680
	ds_read_b128 v[202:205], v135 offset:25600
	ds_read_b128 v[206:209], v135 offset:28160
	s_nop 0
	s_waitcnt lgkmcnt(5)
	v_mfma_f32_16x16x32_bf16 v[124:127], v[186:189], v[178:181], v[124:127]
	v_mfma_f32_16x16x32_bf16 v[108:111], v[186:189], v[182:185], v[108:111]
	s_waitcnt lgkmcnt(3)
	v_mfma_f32_16x16x32_bf16 v[92:95], v[186:189], v[194:197], v[92:95]
	s_waitcnt lgkmcnt(2)
	v_mfma_f32_16x16x32_bf16 v[76:79], v[186:189], v[198:201], v[76:79]
	v_mfma_f32_16x16x32_bf16 v[120:123], v[190:193], v[178:181], v[120:123]
	v_mfma_f32_16x16x32_bf16 v[104:107], v[190:193], v[182:185], v[104:107]
	v_mfma_f32_16x16x32_bf16 v[88:91], v[190:193], v[194:197], v[88:91]
	s_waitcnt lgkmcnt(1)
	v_mfma_f32_16x16x32_bf16 v[116:119], v[202:205], v[178:181], v[116:119]
	v_mfma_f32_16x16x32_bf16 v[100:103], v[202:205], v[182:185], v[100:103]
	s_waitcnt lgkmcnt(0)
	v_mfma_f32_16x16x32_bf16 v[112:115], v[206:209], v[178:181], v[112:115]
	v_mfma_f32_16x16x32_bf16 v[186:189], v[190:193], v[198:201], v[72:75]
	v_mfma_f32_16x16x32_bf16 v[190:193], v[202:205], v[194:197], v[84:87]
	v_mfma_f32_16x16x32_bf16 v[202:205], v[202:205], v[198:201], v[68:71]
	v_mfma_f32_16x16x32_bf16 v[178:181], v[206:209], v[182:185], v[96:99]
	v_mfma_f32_16x16x32_bf16 v[182:185], v[206:209], v[194:197], v[80:83]
	v_mfma_f32_16x16x32_bf16 v[194:197], v[206:209], v[198:201], v[64:67]
	s_nop 0
	ds_read_b128 v[198:201], v134 offset:64
	ds_read_b128 v[206:209], v134 offset:2624
	ds_read_b128 v[80:83], v135 offset:20544
	ds_read_b128 v[96:99], v135 offset:23104
	ds_read_b128 v[210:213], v134 offset:5184
	ds_read_b128 v[214:217], v134 offset:7744
	ds_read_b128 v[218:221], v135 offset:25664
	ds_read_b128 v[222:225], v135 offset:28224
	s_nop 0
	s_waitcnt lgkmcnt(5)
	v_mfma_f32_16x16x32_bf16 v[64:67], v[80:83], v[198:201], v[124:127]
	v_mfma_f32_16x16x32_bf16 v[68:71], v[80:83], v[206:209], v[108:111]
	s_waitcnt lgkmcnt(3)
	v_mfma_f32_16x16x32_bf16 v[72:75], v[80:83], v[210:213], v[92:95]
	s_waitcnt lgkmcnt(2)
	v_mfma_f32_16x16x32_bf16 v[76:79], v[80:83], v[214:217], v[76:79]
	v_mfma_f32_16x16x32_bf16 v[80:83], v[96:99], v[198:201], v[120:123]
	v_mfma_f32_16x16x32_bf16 v[84:87], v[96:99], v[206:209], v[104:107]
	v_mfma_f32_16x16x32_bf16 v[88:91], v[96:99], v[210:213], v[88:91]
	v_mfma_f32_16x16x32_bf16 v[92:95], v[96:99], v[214:217], v[186:189]
	s_waitcnt lgkmcnt(1)
	v_mfma_f32_16x16x32_bf16 v[96:99], v[218:221], v[198:201], v[116:119]
	v_mfma_f32_16x16x32_bf16 v[100:103], v[218:221], v[206:209], v[100:103]
	v_mfma_f32_16x16x32_bf16 v[104:107], v[218:221], v[210:213], v[190:193]
	v_mfma_f32_16x16x32_bf16 v[108:111], v[218:221], v[214:217], v[202:205]
	s_waitcnt lgkmcnt(0)
	v_mfma_f32_16x16x32_bf16 v[112:115], v[222:225], v[198:201], v[112:115]
	v_mfma_f32_16x16x32_bf16 v[116:119], v[222:225], v[206:209], v[178:181]
	v_mfma_f32_16x16x32_bf16 v[120:123], v[222:225], v[210:213], v[182:185]
	v_mfma_f32_16x16x32_bf16 v[124:127], v[222:225], v[214:217], v[194:197]
	s_nop 0
	s_cmp_gt_u32 s2, 5
	s_cselect_b64 s[0:1], -1, 0
	s_cmp_lt_u32 s2, 6
	s_cselect_b64 s[4:5], -1, 0
	s_or_b64 s[4:5], s[10:11], s[4:5]
	s_andn2_b64 vcc, exec, s[4:5]
	s_barrier
	s_cbranch_vccnz .LBB0_855
	s_waitcnt vmcnt(15)
	ds_write_b128 v155, v[4:7]
	s_waitcnt vmcnt(14)
	ds_write_b128 v155, v[12:15] offset:20480
	s_waitcnt vmcnt(13)
	ds_write_b128 v156, v[20:23]
	s_waitcnt vmcnt(12)
	ds_write_b128 v156, v[32:35] offset:20480
	s_waitcnt vmcnt(11)
	ds_write_b128 v157, v[40:43]
	s_waitcnt vmcnt(10)
	ds_write_b128 v157, v[48:51] offset:20480
	s_waitcnt vmcnt(9)
	ds_write_b128 v158, v[52:55]
	s_waitcnt vmcnt(8)
	ds_write_b128 v158, v[60:63] offset:20480

.LBB0_988:
	s_waitcnt vmcnt(15)
	v_lshl_add_u64 v[60:61], v[130:131], 1, s[86:87]
	global_load_dwordx4 v[60:63], v[60:61], off
	ds_read_b128 v[170:173], v132 offset:40960
	ds_read_b128 v[174:177], v132 offset:43520
	ds_read_b128 v[178:181], v133 offset:61440
	ds_read_b128 v[182:185], v133 offset:64000
	ds_read_b128 v[186:189], v132 offset:46080
	ds_read_b128 v[190:193], v132 offset:48640
	ds_read_b128 v[194:197], v150 offset:5120
	ds_read_b128 v[198:201], v150 offset:7680
	s_nop 0
	s_waitcnt lgkmcnt(5)
	v_mfma_f32_16x16x32_bf16 v[64:67], v[178:181], v[170:173], v[64:67]
	v_mfma_f32_16x16x32_bf16 v[68:71], v[178:181], v[174:177], v[68:71]
	s_waitcnt lgkmcnt(3)
	v_mfma_f32_16x16x32_bf16 v[72:75], v[178:181], v[186:189], v[72:75]
	s_waitcnt lgkmcnt(2)
	v_mfma_f32_16x16x32_bf16 v[76:79], v[178:181], v[190:193], v[76:79]
	v_mfma_f32_16x16x32_bf16 v[80:83], v[182:185], v[170:173], v[80:83]
	v_mfma_f32_16x16x32_bf16 v[84:87], v[182:185], v[174:177], v[84:87]
	v_mfma_f32_16x16x32_bf16 v[88:91], v[182:185], v[186:189], v[88:91]
	v_mfma_f32_16x16x32_bf16 v[92:95], v[182:185], v[190:193], v[92:95]
	s_waitcnt lgkmcnt(1)
	v_mfma_f32_16x16x32_bf16 v[178:181], v[194:197], v[170:173], v[96:99]
	v_mfma_f32_16x16x32_bf16 v[182:185], v[194:197], v[174:177], v[100:103]
	v_mfma_f32_16x16x32_bf16 v[202:205], v[194:197], v[186:189], v[104:107]
	v_mfma_f32_16x16x32_bf16 v[194:197], v[194:197], v[190:193], v[108:111]
	s_waitcnt lgkmcnt(0)
	v_mfma_f32_16x16x32_bf16 v[170:173], v[198:201], v[170:173], v[112:115]
	v_mfma_f32_16x16x32_bf16 v[174:177], v[198:201], v[174:177], v[116:119]
	v_mfma_f32_16x16x32_bf16 v[186:189], v[198:201], v[186:189], v[120:123]
	v_mfma_f32_16x16x32_bf16 v[190:193], v[198:201], v[190:193], v[124:127]
	s_nop 0
	ds_read_b128 v[198:201], v132 offset:41024
	ds_read_b128 v[206:209], v132 offset:43584
	ds_read_b128 v[96:99], v133 offset:61504
	ds_read_b128 v[210:213], v133 offset:64064
	ds_read_b128 v[214:217], v132 offset:46144
	ds_read_b128 v[218:221], v132 offset:48704
	ds_read_b128 v[222:225], v151 offset:5120
	ds_read_b128 v[226:229], v151 offset:7680
	s_nop 0
	s_waitcnt lgkmcnt(5)
	v_mfma_f32_16x16x32_bf16 v[124:127], v[96:99], v[198:201], v[64:67]
	v_mfma_f32_16x16x32_bf16 v[120:123], v[96:99], v[206:209], v[68:71]
	s_waitcnt lgkmcnt(3)
	v_mfma_f32_16x16x32_bf16 v[116:119], v[96:99], v[214:217], v[72:75]
	s_waitcnt lgkmcnt(2)
	v_mfma_f32_16x16x32_bf16 v[112:115], v[96:99], v[218:221], v[76:79]
	v_mfma_f32_16x16x32_bf16 v[108:111], v[210:213], v[198:201], v[80:83]
	v_mfma_f32_16x16x32_bf16 v[104:107], v[210:213], v[206:209], v[84:87]
	v_mfma_f32_16x16x32_bf16 v[100:103], v[210:213], v[214:217], v[88:91]
	v_mfma_f32_16x16x32_bf16 v[96:99], v[210:213], v[218:221], v[92:95]
	s_waitcnt lgkmcnt(1)
	v_mfma_f32_16x16x32_bf16 v[92:95], v[222:225], v[198:201], v[178:181]
	v_mfma_f32_16x16x32_bf16 v[88:91], v[222:225], v[206:209], v[182:185]
	v_mfma_f32_16x16x32_bf16 v[84:87], v[222:225], v[214:217], v[202:205]
	v_mfma_f32_16x16x32_bf16 v[80:83], v[222:225], v[218:221], v[194:197]
	s_waitcnt lgkmcnt(0)
	v_mfma_f32_16x16x32_bf16 v[76:79], v[226:229], v[198:201], v[170:173]
	v_mfma_f32_16x16x32_bf16 v[72:75], v[226:229], v[206:209], v[174:177]
	v_mfma_f32_16x16x32_bf16 v[68:71], v[226:229], v[214:217], v[186:189]
	v_mfma_f32_16x16x32_bf16 v[64:67], v[226:229], v[218:221], v[190:193]
	s_nop 0
	s_add_i32 s23, s23, 2
	s_addk_i32 s22, 0x80
	s_addk_i32 s21, 0x80
	v_add_u32_e32 v161, 0x80, v161
	v_add_u32_e32 v162, 0x80, v162
	v_add_u32_e32 v163, 0x80, v163
	v_add_u32_e32 v164, 0x80, v164
	s_addk_i32 s20, 0x80
	v_add_u32_e32 v165, 0x80, v165
	v_add_u32_e32 v166, 0x80, v166
	v_add_u32_e32 v167, 0x80, v167
	v_add_u32_e32 v168, 0x80, v168
	s_and_b64 vcc, exec, s[8:9]
	s_cbranch_vccnz .LBB0_1007

.LBB0_997:
	s_nop 0
	v_lshl_add_u64 v[56:57], v[130:131], 1, s[86:87]
	global_load_dwordx4 v[56:59], v[56:57], off
	ds_read_b128 v[170:173], v132
	ds_read_b128 v[174:177], v132 offset:2560
	ds_read_b128 v[178:181], v133 offset:20480
	ds_read_b128 v[182:185], v133 offset:23040
	ds_read_b128 v[186:189], v132 offset:5120
	ds_read_b128 v[190:193], v132 offset:7680
	ds_read_b128 v[194:197], v133 offset:25600
	ds_read_b128 v[198:201], v133 offset:28160
	s_nop 0
	s_waitcnt lgkmcnt(5)
	v_mfma_f32_16x16x32_bf16 v[124:127], v[178:181], v[170:173], v[124:127]
	v_mfma_f32_16x16x32_bf16 v[120:123], v[178:181], v[174:177], v[120:123]
	s_waitcnt lgkmcnt(3)
	v_mfma_f32_16x16x32_bf16 v[116:119], v[178:181], v[186:189], v[116:119]
	s_waitcnt lgkmcnt(2)
	v_mfma_f32_16x16x32_bf16 v[112:115], v[178:181], v[190:193], v[112:115]
	v_mfma_f32_16x16x32_bf16 v[108:111], v[182:185], v[170:173], v[108:111]
	v_mfma_f32_16x16x32_bf16 v[104:107], v[182:185], v[174:177], v[104:107]
	v_mfma_f32_16x16x32_bf16 v[100:103], v[182:185], v[186:189], v[100:103]
	v_mfma_f32_16x16x32_bf16 v[96:99], v[182:185], v[190:193], v[96:99]
	s_waitcnt lgkmcnt(1)
	v_mfma_f32_16x16x32_bf16 v[178:181], v[194:197], v[170:173], v[92:95]
	v_mfma_f32_16x16x32_bf16 v[182:185], v[194:197], v[174:177], v[88:91]
	v_mfma_f32_16x16x32_bf16 v[202:205], v[194:197], v[186:189], v[84:87]
	v_mfma_f32_16x16x32_bf16 v[194:197], v[194:197], v[190:193], v[80:83]
	s_waitcnt lgkmcnt(0)
	v_mfma_f32_16x16x32_bf16 v[170:173], v[198:201], v[170:173], v[76:79]
	v_mfma_f32_16x16x32_bf16 v[174:177], v[198:201], v[174:177], v[72:75]
	v_mfma_f32_16x16x32_bf16 v[186:189], v[198:201], v[186:189], v[68:71]
	v_mfma_f32_16x16x32_bf16 v[190:193], v[198:201], v[190:193], v[64:67]
	s_nop 0
	ds_read_b128 v[198:201], v132 offset:64
	ds_read_b128 v[206:209], v132 offset:2624
	ds_read_b128 v[76:79], v133 offset:20544
	ds_read_b128 v[92:95], v133 offset:23104
	ds_read_b128 v[210:213], v132 offset:5184
	ds_read_b128 v[214:217], v132 offset:7744
	ds_read_b128 v[218:221], v133 offset:25664
	ds_read_b128 v[222:225], v133 offset:28224
	s_nop 0
	s_waitcnt lgkmcnt(5)
	v_mfma_f32_16x16x32_bf16 v[64:67], v[76:79], v[198:201], v[124:127]
	v_mfma_f32_16x16x32_bf16 v[68:71], v[76:79], v[206:209], v[120:123]
	s_waitcnt lgkmcnt(3)
	v_mfma_f32_16x16x32_bf16 v[72:75], v[76:79], v[210:213], v[116:119]
	s_waitcnt lgkmcnt(2)
	v_mfma_f32_16x16x32_bf16 v[76:79], v[76:79], v[214:217], v[112:115]
	v_mfma_f32_16x16x32_bf16 v[80:83], v[92:95], v[198:201], v[108:111]
	v_mfma_f32_16x16x32_bf16 v[84:87], v[92:95], v[206:209], v[104:107]
	v_mfma_f32_16x16x32_bf16 v[88:91], v[92:95], v[210:213], v[100:103]
	v_mfma_f32_16x16x32_bf16 v[92:95], v[92:95], v[214:217], v[96:99]
	s_waitcnt lgkmcnt(1)
	v_mfma_f32_16x16x32_bf16 v[96:99], v[218:221], v[198:201], v[178:181]
	v_mfma_f32_16x16x32_bf16 v[100:103], v[218:221], v[206:209], v[182:185]
	v_mfma_f32_16x16x32_bf16 v[104:107], v[218:221], v[210:213], v[202:205]
	v_mfma_f32_16x16x32_bf16 v[108:111], v[218:221], v[214:217], v[194:197]
	s_waitcnt lgkmcnt(0)
	v_mfma_f32_16x16x32_bf16 v[112:115], v[222:225], v[198:201], v[170:173]
	v_mfma_f32_16x16x32_bf16 v[116:119], v[222:225], v[206:209], v[174:177]
	v_mfma_f32_16x16x32_bf16 v[120:123], v[222:225], v[210:213], v[186:189]
	v_mfma_f32_16x16x32_bf16 v[124:127], v[222:225], v[214:217], v[190:193]
	s_nop 0
	s_cmp_gt_u32 s23, 13
	s_cselect_b64 s[8:9], -1, 0
	s_cmp_lt_u32 s23, 14
	s_cselect_b64 s[10:11], -1, 0
	s_or_b64 s[10:11], s[6:7], s[10:11]
	s_andn2_b64 vcc, exec, s[10:11]
	s_barrier
	s_cbranch_vccnz .LBB0_999
	s_waitcnt vmcnt(15)
	ds_write_b128 v146, v[4:7]
	s_waitcnt vmcnt(14)
	ds_write_b128 v146, v[12:15] offset:20480
	s_waitcnt vmcnt(13)
	ds_write_b128 v147, v[20:23]
	s_waitcnt vmcnt(12)
	ds_write_b128 v147, v[32:35] offset:20480
	s_waitcnt vmcnt(11)
	ds_write_b128 v148, v[40:43]
	s_waitcnt vmcnt(10)
	ds_write_b128 v148, v[48:51] offset:20480
	s_waitcnt vmcnt(9)
	ds_write_b128 v149, v[52:55]
	s_waitcnt vmcnt(8)
	ds_write_b128 v149, v[60:63] offset:20480

.LBB0_1598:
	s_waitcnt vmcnt(15)
	v_lshl_add_u64 v[60:61], v[130:131], 1, s[84:85]
	global_load_dwordx4 v[60:63], v[60:61], off
	ds_read_b128 v[160:163], v134 offset:40960
	ds_read_b128 v[164:167], v134 offset:43520
	ds_read_b128 v[168:171], v135 offset:61440
	ds_read_b128 v[172:175], v135 offset:64000
	ds_read_b128 v[176:179], v134 offset:46080
	ds_read_b128 v[180:183], v134 offset:48640
	ds_read_b128 v[184:187], v149 offset:5120
	ds_read_b128 v[188:191], v149 offset:7680
	s_nop 0
	s_waitcnt lgkmcnt(5)
	v_mfma_f32_16x16x32_bf16 v[64:67], v[168:171], v[160:163], v[64:67]
	v_mfma_f32_16x16x32_bf16 v[68:71], v[168:171], v[164:167], v[68:71]
	s_waitcnt lgkmcnt(3)
	v_mfma_f32_16x16x32_bf16 v[72:75], v[168:171], v[176:179], v[72:75]
	s_waitcnt lgkmcnt(2)
	v_mfma_f32_16x16x32_bf16 v[76:79], v[168:171], v[180:183], v[76:79]
	v_mfma_f32_16x16x32_bf16 v[80:83], v[172:175], v[160:163], v[80:83]
	v_mfma_f32_16x16x32_bf16 v[84:87], v[172:175], v[164:167], v[84:87]
	v_mfma_f32_16x16x32_bf16 v[88:91], v[172:175], v[176:179], v[88:91]
	v_mfma_f32_16x16x32_bf16 v[92:95], v[172:175], v[180:183], v[92:95]
	s_waitcnt lgkmcnt(1)
	v_mfma_f32_16x16x32_bf16 v[168:171], v[184:187], v[160:163], v[96:99]
	v_mfma_f32_16x16x32_bf16 v[172:175], v[184:187], v[164:167], v[100:103]
	v_mfma_f32_16x16x32_bf16 v[192:195], v[184:187], v[176:179], v[104:107]
	v_mfma_f32_16x16x32_bf16 v[184:187], v[184:187], v[180:183], v[108:111]
	s_waitcnt lgkmcnt(0)
	v_mfma_f32_16x16x32_bf16 v[160:163], v[188:191], v[160:163], v[112:115]
	v_mfma_f32_16x16x32_bf16 v[164:167], v[188:191], v[164:167], v[116:119]
	v_mfma_f32_16x16x32_bf16 v[176:179], v[188:191], v[176:179], v[120:123]
	v_mfma_f32_16x16x32_bf16 v[180:183], v[188:191], v[180:183], v[124:127]
	s_nop 0
	ds_read_b128 v[188:191], v134 offset:41024
	ds_read_b128 v[196:199], v134 offset:43584
	ds_read_b128 v[96:99], v135 offset:61504
	ds_read_b128 v[200:203], v135 offset:64064
	ds_read_b128 v[204:207], v134 offset:46144
	ds_read_b128 v[208:211], v134 offset:48704
	ds_read_b128 v[212:215], v150 offset:5120
	ds_read_b128 v[216:219], v150 offset:7680
	s_nop 0
	s_waitcnt lgkmcnt(5)
	v_mfma_f32_16x16x32_bf16 v[124:127], v[96:99], v[188:191], v[64:67]
	v_mfma_f32_16x16x32_bf16 v[120:123], v[96:99], v[196:199], v[68:71]
	s_waitcnt lgkmcnt(3)
	v_mfma_f32_16x16x32_bf16 v[116:119], v[96:99], v[204:207], v[72:75]
	s_waitcnt lgkmcnt(2)
	v_mfma_f32_16x16x32_bf16 v[112:115], v[96:99], v[208:211], v[76:79]
	v_mfma_f32_16x16x32_bf16 v[108:111], v[200:203], v[188:191], v[80:83]
	v_mfma_f32_16x16x32_bf16 v[104:107], v[200:203], v[196:199], v[84:87]
	v_mfma_f32_16x16x32_bf16 v[100:103], v[200:203], v[204:207], v[88:91]
	v_mfma_f32_16x16x32_bf16 v[96:99], v[200:203], v[208:211], v[92:95]
	s_waitcnt lgkmcnt(1)
	v_mfma_f32_16x16x32_bf16 v[92:95], v[212:215], v[188:191], v[168:171]
	v_mfma_f32_16x16x32_bf16 v[88:91], v[212:215], v[196:199], v[172:175]
	v_mfma_f32_16x16x32_bf16 v[84:87], v[212:215], v[204:207], v[192:195]
	v_mfma_f32_16x16x32_bf16 v[80:83], v[212:215], v[208:211], v[184:187]
	s_waitcnt lgkmcnt(0)
	v_mfma_f32_16x16x32_bf16 v[76:79], v[216:219], v[188:191], v[160:163]
	v_mfma_f32_16x16x32_bf16 v[72:75], v[216:219], v[196:199], v[164:167]
	v_mfma_f32_16x16x32_bf16 v[68:71], v[216:219], v[204:207], v[176:179]
	v_mfma_f32_16x16x32_bf16 v[64:67], v[216:219], v[208:211], v[180:183]
	s_nop 0
	s_add_i32 s15, s15, 2
	v_add_u32_e32 v143, 0x80, v143
	v_add_u32_e32 v142, 0x80, v142
	v_add_u32_e32 v140, 0x80, v140
	s_andn2_b64 vcc, exec, s[4:5]
	v_add_u32_e32 v138, 0x80, v138
	s_cbranch_vccz .LBB0_1592

.LBB0_1607:
	s_nop 0
	v_lshl_add_u64 v[56:57], v[130:131], 1, s[84:85]
	global_load_dwordx4 v[56:59], v[56:57], off
	ds_read_b128 v[162:165], v134
	ds_read_b128 v[166:169], v134 offset:2560
	ds_read_b128 v[170:173], v135 offset:20480
	ds_read_b128 v[174:177], v135 offset:23040
	ds_read_b128 v[178:181], v134 offset:5120
	ds_read_b128 v[182:185], v134 offset:7680
	ds_read_b128 v[186:189], v135 offset:25600
	ds_read_b128 v[190:193], v135 offset:28160
	s_nop 0
	s_waitcnt lgkmcnt(5)
	v_mfma_f32_16x16x32_bf16 v[124:127], v[170:173], v[162:165], v[124:127]
	v_mfma_f32_16x16x32_bf16 v[120:123], v[170:173], v[166:169], v[120:123]
	s_waitcnt lgkmcnt(3)
	v_mfma_f32_16x16x32_bf16 v[116:119], v[170:173], v[178:181], v[116:119]
	s_waitcnt lgkmcnt(2)
	v_mfma_f32_16x16x32_bf16 v[112:115], v[170:173], v[182:185], v[112:115]
	v_mfma_f32_16x16x32_bf16 v[108:111], v[174:177], v[162:165], v[108:111]
	v_mfma_f32_16x16x32_bf16 v[104:107], v[174:177], v[166:169], v[104:107]
	v_mfma_f32_16x16x32_bf16 v[100:103], v[174:177], v[178:181], v[100:103]
	v_mfma_f32_16x16x32_bf16 v[96:99], v[174:177], v[182:185], v[96:99]
	s_waitcnt lgkmcnt(1)
	v_mfma_f32_16x16x32_bf16 v[170:173], v[186:189], v[162:165], v[92:95]
	v_mfma_f32_16x16x32_bf16 v[174:177], v[186:189], v[166:169], v[88:91]
	v_mfma_f32_16x16x32_bf16 v[194:197], v[186:189], v[178:181], v[84:87]
	v_mfma_f32_16x16x32_bf16 v[186:189], v[186:189], v[182:185], v[80:83]
	s_waitcnt lgkmcnt(0)
	v_mfma_f32_16x16x32_bf16 v[162:165], v[190:193], v[162:165], v[76:79]
	v_mfma_f32_16x16x32_bf16 v[166:169], v[190:193], v[166:169], v[72:75]
	v_mfma_f32_16x16x32_bf16 v[178:181], v[190:193], v[178:181], v[68:71]
	v_mfma_f32_16x16x32_bf16 v[182:185], v[190:193], v[182:185], v[64:67]
	s_nop 0
	ds_read_b128 v[190:193], v134 offset:64
	ds_read_b128 v[198:201], v134 offset:2624
	ds_read_b128 v[76:79], v135 offset:20544
	ds_read_b128 v[92:95], v135 offset:23104
	ds_read_b128 v[202:205], v134 offset:5184
	ds_read_b128 v[206:209], v134 offset:7744
	ds_read_b128 v[210:213], v135 offset:25664
	ds_read_b128 v[214:217], v135 offset:28224
	s_nop 0
	s_waitcnt lgkmcnt(5)
	v_mfma_f32_16x16x32_bf16 v[64:67], v[76:79], v[190:193], v[124:127]
	v_mfma_f32_16x16x32_bf16 v[68:71], v[76:79], v[198:201], v[120:123]
	s_waitcnt lgkmcnt(3)
	v_mfma_f32_16x16x32_bf16 v[72:75], v[76:79], v[202:205], v[116:119]
	s_waitcnt lgkmcnt(2)
	v_mfma_f32_16x16x32_bf16 v[76:79], v[76:79], v[206:209], v[112:115]
	v_mfma_f32_16x16x32_bf16 v[80:83], v[92:95], v[190:193], v[108:111]
	v_mfma_f32_16x16x32_bf16 v[84:87], v[92:95], v[198:201], v[104:107]
	v_mfma_f32_16x16x32_bf16 v[88:91], v[92:95], v[202:205], v[100:103]
	v_mfma_f32_16x16x32_bf16 v[92:95], v[92:95], v[206:209], v[96:99]
	s_waitcnt lgkmcnt(1)
	v_mfma_f32_16x16x32_bf16 v[96:99], v[210:213], v[190:193], v[170:173]
	v_mfma_f32_16x16x32_bf16 v[100:103], v[210:213], v[198:201], v[174:177]
	v_mfma_f32_16x16x32_bf16 v[104:107], v[210:213], v[202:205], v[194:197]
	v_mfma_f32_16x16x32_bf16 v[108:111], v[210:213], v[206:209], v[186:189]
	s_waitcnt lgkmcnt(0)
	v_mfma_f32_16x16x32_bf16 v[112:115], v[214:217], v[190:193], v[162:165]
	v_mfma_f32_16x16x32_bf16 v[116:119], v[214:217], v[198:201], v[166:169]
	v_mfma_f32_16x16x32_bf16 v[120:123], v[214:217], v[202:205], v[178:181]
	v_mfma_f32_16x16x32_bf16 v[124:127], v[214:217], v[206:209], v[182:185]
	s_nop 0
	s_cmp_gt_u32 s15, 13
	s_cselect_b64 s[4:5], -1, 0
	s_cmp_lt_u32 s15, 14
	s_cselect_b64 s[6:7], -1, 0
	s_or_b64 s[6:7], s[2:3], s[6:7]
	s_andn2_b64 vcc, exec, s[6:7]
	s_barrier
	s_cbranch_vccnz .LBB0_1609
	s_waitcnt vmcnt(15)
	ds_write_b128 v144, v[4:7]
	s_waitcnt vmcnt(14)
	ds_write_b128 v144, v[12:15] offset:20480
	s_waitcnt vmcnt(13)
	ds_write_b128 v145, v[20:23]
	s_waitcnt vmcnt(12)
	ds_write_b128 v145, v[32:35] offset:20480
	s_waitcnt vmcnt(11)
	ds_write_b128 v146, v[40:43]
	s_waitcnt vmcnt(10)
	ds_write_b128 v146, v[48:51] offset:20480
	s_waitcnt vmcnt(9)
	ds_write_b128 v147, v[52:55]
	s_waitcnt vmcnt(8)
	ds_write_b128 v147, v[60:63] offset:20480

.LBB0_1828:
	s_waitcnt vmcnt(15)
	v_lshl_add_u64 v[60:61], v[130:131], 1, s[92:93]
	global_load_dwordx4 v[60:63], v[60:61], off
	ds_read_b128 v[184:187], v136 offset:40960
	ds_read_b128 v[188:191], v136 offset:43520
	ds_read_b128 v[192:195], v137 offset:61440
	ds_read_b128 v[196:199], v137 offset:64000
	ds_read_b128 v[200:203], v136 offset:46080
	ds_read_b128 v[204:207], v136 offset:48640
	ds_read_b128 v[208:211], v161
	ds_read_b128 v[212:215], v162
	s_nop 0
	s_waitcnt lgkmcnt(5)
	v_mfma_f32_16x16x32_bf16 v[64:67], v[192:195], v[184:187], v[64:67]
	v_mfma_f32_16x16x32_bf16 v[68:71], v[192:195], v[188:191], v[68:71]
	s_waitcnt lgkmcnt(3)
	v_mfma_f32_16x16x32_bf16 v[72:75], v[192:195], v[200:203], v[72:75]
	s_waitcnt lgkmcnt(2)
	v_mfma_f32_16x16x32_bf16 v[76:79], v[192:195], v[204:207], v[76:79]
	v_mfma_f32_16x16x32_bf16 v[80:83], v[196:199], v[184:187], v[80:83]
	v_mfma_f32_16x16x32_bf16 v[84:87], v[196:199], v[188:191], v[84:87]
	v_mfma_f32_16x16x32_bf16 v[88:91], v[196:199], v[200:203], v[88:91]
	s_waitcnt lgkmcnt(1)
	v_mfma_f32_16x16x32_bf16 v[96:99], v[208:211], v[184:187], v[96:99]
	v_mfma_f32_16x16x32_bf16 v[100:103], v[208:211], v[188:191], v[100:103]
	s_waitcnt lgkmcnt(0)
	v_mfma_f32_16x16x32_bf16 v[112:115], v[212:215], v[184:187], v[112:115]
	v_mfma_f32_16x16x32_bf16 v[192:195], v[196:199], v[204:207], v[92:95]
	v_mfma_f32_16x16x32_bf16 v[196:199], v[208:211], v[200:203], v[104:107]
	v_mfma_f32_16x16x32_bf16 v[208:211], v[208:211], v[204:207], v[108:111]
	v_mfma_f32_16x16x32_bf16 v[184:187], v[212:215], v[188:191], v[116:119]
	v_mfma_f32_16x16x32_bf16 v[188:191], v[212:215], v[200:203], v[120:123]
	v_mfma_f32_16x16x32_bf16 v[200:203], v[212:215], v[204:207], v[124:127]
	s_nop 0
	ds_read_b128 v[204:207], v136 offset:41024
	ds_read_b128 v[212:215], v136 offset:43584
	ds_read_b128 v[104:107], v137 offset:61504
	ds_read_b128 v[116:119], v137 offset:64064
	ds_read_b128 v[216:219], v136 offset:46144
	ds_read_b128 v[220:223], v136 offset:48704
	ds_read_b128 v[224:227], v163
	ds_read_b128 v[228:231], v164
	s_nop 0
	s_waitcnt lgkmcnt(5)
	v_mfma_f32_16x16x32_bf16 v[124:127], v[104:107], v[204:207], v[64:67]
	v_mfma_f32_16x16x32_bf16 v[108:111], v[104:107], v[212:215], v[68:71]
	s_waitcnt lgkmcnt(3)
	v_mfma_f32_16x16x32_bf16 v[92:95], v[104:107], v[216:219], v[72:75]
	s_waitcnt lgkmcnt(2)
	v_mfma_f32_16x16x32_bf16 v[76:79], v[104:107], v[220:223], v[76:79]
	v_mfma_f32_16x16x32_bf16 v[120:123], v[116:119], v[204:207], v[80:83]
	v_mfma_f32_16x16x32_bf16 v[104:107], v[116:119], v[212:215], v[84:87]
	v_mfma_f32_16x16x32_bf16 v[88:91], v[116:119], v[216:219], v[88:91]
	v_mfma_f32_16x16x32_bf16 v[72:75], v[116:119], v[220:223], v[192:195]
	s_waitcnt lgkmcnt(1)
	v_mfma_f32_16x16x32_bf16 v[116:119], v[224:227], v[204:207], v[96:99]
	v_mfma_f32_16x16x32_bf16 v[100:103], v[224:227], v[212:215], v[100:103]
	v_mfma_f32_16x16x32_bf16 v[84:87], v[224:227], v[216:219], v[196:199]
	v_mfma_f32_16x16x32_bf16 v[68:71], v[224:227], v[220:223], v[208:211]
	s_waitcnt lgkmcnt(0)
	v_mfma_f32_16x16x32_bf16 v[112:115], v[228:231], v[204:207], v[112:115]
	v_mfma_f32_16x16x32_bf16 v[96:99], v[228:231], v[212:215], v[184:187]
	v_mfma_f32_16x16x32_bf16 v[80:83], v[228:231], v[216:219], v[188:191]
	v_mfma_f32_16x16x32_bf16 v[64:67], v[228:231], v[220:223], v[200:203]
	s_nop 0
	s_add_i32 s10, s10, 2
	v_add_u32_e32 v182, 0x80, v182
	v_add_u32_e32 v181, 0x80, v181
	v_add_u32_e32 v180, 0x80, v180
	v_add_u32_e32 v179, 0x80, v179
	v_add_u32_e32 v178, 0x80, v178
	v_add_u32_e32 v177, 0x80, v177
	v_add_u32_e32 v176, 0x80, v176
	v_add_u32_e32 v175, 0x80, v175
	v_add_u32_e32 v174, 0x80, v174
	v_add_u32_e32 v173, 0x80, v173
	s_and_b64 vcc, exec, s[0:1]
	s_cbranch_vccnz .LBB0_1847

.LBB0_1837:
	s_nop 0
	v_lshl_add_u64 v[56:57], v[130:131], 1, s[92:93]
	global_load_dwordx4 v[56:59], v[56:57], off
	ds_read_b128 v[184:187], v136
	ds_read_b128 v[188:191], v136 offset:2560
	ds_read_b128 v[192:195], v137 offset:20480
	ds_read_b128 v[196:199], v137 offset:23040
	ds_read_b128 v[200:203], v136 offset:5120
	ds_read_b128 v[204:207], v136 offset:7680
	ds_read_b128 v[208:211], v137 offset:25600
	ds_read_b128 v[212:215], v137 offset:28160
	s_nop 0
	s_waitcnt lgkmcnt(5)
	v_mfma_f32_16x16x32_bf16 v[124:127], v[192:195], v[184:187], v[124:127]
	v_mfma_f32_16x16x32_bf16 v[108:111], v[192:195], v[188:191], v[108:111]
	s_waitcnt lgkmcnt(3)
	v_mfma_f32_16x16x32_bf16 v[92:95], v[192:195], v[200:203], v[92:95]
	s_waitcnt lgkmcnt(2)
	v_mfma_f32_16x16x32_bf16 v[76:79], v[192:195], v[204:207], v[76:79]
	v_mfma_f32_16x16x32_bf16 v[120:123], v[196:199], v[184:187], v[120:123]
	v_mfma_f32_16x16x32_bf16 v[104:107], v[196:199], v[188:191], v[104:107]
	v_mfma_f32_16x16x32_bf16 v[88:91], v[196:199], v[200:203], v[88:91]
	s_waitcnt lgkmcnt(1)
	v_mfma_f32_16x16x32_bf16 v[116:119], v[208:211], v[184:187], v[116:119]
	v_mfma_f32_16x16x32_bf16 v[100:103], v[208:211], v[188:191], v[100:103]
	s_waitcnt lgkmcnt(0)
	v_mfma_f32_16x16x32_bf16 v[112:115], v[212:215], v[184:187], v[112:115]
	v_mfma_f32_16x16x32_bf16 v[192:195], v[196:199], v[204:207], v[72:75]
	v_mfma_f32_16x16x32_bf16 v[196:199], v[208:211], v[200:203], v[84:87]
	v_mfma_f32_16x16x32_bf16 v[208:211], v[208:211], v[204:207], v[68:71]
	v_mfma_f32_16x16x32_bf16 v[184:187], v[212:215], v[188:191], v[96:99]
	v_mfma_f32_16x16x32_bf16 v[188:191], v[212:215], v[200:203], v[80:83]
	v_mfma_f32_16x16x32_bf16 v[200:203], v[212:215], v[204:207], v[64:67]
	s_nop 0
	ds_read_b128 v[204:207], v136 offset:64
	ds_read_b128 v[212:215], v136 offset:2624
	ds_read_b128 v[80:83], v137 offset:20544
	ds_read_b128 v[96:99], v137 offset:23104
	ds_read_b128 v[216:219], v136 offset:5184
	ds_read_b128 v[220:223], v136 offset:7744
	ds_read_b128 v[224:227], v137 offset:25664
	ds_read_b128 v[228:231], v137 offset:28224
	s_nop 0
	s_waitcnt lgkmcnt(5)
	v_mfma_f32_16x16x32_bf16 v[64:67], v[80:83], v[204:207], v[124:127]
	v_mfma_f32_16x16x32_bf16 v[68:71], v[80:83], v[212:215], v[108:111]
	s_waitcnt lgkmcnt(3)
	v_mfma_f32_16x16x32_bf16 v[72:75], v[80:83], v[216:219], v[92:95]
	s_waitcnt lgkmcnt(2)
	v_mfma_f32_16x16x32_bf16 v[76:79], v[80:83], v[220:223], v[76:79]
	v_mfma_f32_16x16x32_bf16 v[80:83], v[96:99], v[204:207], v[120:123]
	v_mfma_f32_16x16x32_bf16 v[84:87], v[96:99], v[212:215], v[104:107]
	v_mfma_f32_16x16x32_bf16 v[88:91], v[96:99], v[216:219], v[88:91]
	v_mfma_f32_16x16x32_bf16 v[92:95], v[96:99], v[220:223], v[192:195]
	s_waitcnt lgkmcnt(1)
	v_mfma_f32_16x16x32_bf16 v[96:99], v[224:227], v[204:207], v[116:119]
	v_mfma_f32_16x16x32_bf16 v[100:103], v[224:227], v[212:215], v[100:103]
	v_mfma_f32_16x16x32_bf16 v[104:107], v[224:227], v[216:219], v[196:199]
	v_mfma_f32_16x16x32_bf16 v[108:111], v[224:227], v[220:223], v[208:211]
	s_waitcnt lgkmcnt(0)
	v_mfma_f32_16x16x32_bf16 v[112:115], v[228:231], v[204:207], v[112:115]
	v_mfma_f32_16x16x32_bf16 v[116:119], v[228:231], v[212:215], v[184:187]
	v_mfma_f32_16x16x32_bf16 v[120:123], v[228:231], v[216:219], v[188:191]
	v_mfma_f32_16x16x32_bf16 v[124:127], v[228:231], v[220:223], v[200:203]
	s_nop 0
	s_cmp_gt_u32 s10, 13
	s_cselect_b64 s[0:1], -1, 0
	s_cmp_lt_u32 s10, 14
	s_cselect_b64 s[8:9], -1, 0
	s_or_b64 s[8:9], s[6:7], s[8:9]
	s_andn2_b64 vcc, exec, s[8:9]
	s_barrier
	s_cbranch_vccnz .LBB0_1839
	s_waitcnt vmcnt(15)
	ds_write_b128 v157, v[4:7]
	s_waitcnt vmcnt(14)
	ds_write_b128 v157, v[12:15] offset:20480
	s_waitcnt vmcnt(13)
	ds_write_b128 v158, v[20:23]
	s_waitcnt vmcnt(12)
	ds_write_b128 v158, v[32:35] offset:20480
	s_waitcnt vmcnt(11)
	ds_write_b128 v159, v[40:43]
	s_waitcnt vmcnt(10)
	ds_write_b128 v159, v[48:51] offset:20480
	s_waitcnt vmcnt(9)
	ds_write_b128 v160, v[52:55]
	s_waitcnt vmcnt(8)
	ds_write_b128 v160, v[60:63] offset:20480

.LBB0_1967:
	v_lshlrev_b32_e32 v65, 1, v136
	v_lshl_add_u32 v155, v74, 1, v65
	v_lshl_add_u32 v156, v71, 1, v65
	v_lshl_add_u32 v157, v72, 1, v65
	v_lshl_add_u32 v158, v73, 1, v65
	v_or_b32_e32 v65, 0xc0, v136
	s_waitcnt lgkmcnt(0)
	s_barrier
	s_waitcnt vmcnt(15)
	ds_write_b128 v155, v[0:3] offset:40960
	s_waitcnt vmcnt(14)
	ds_write_b128 v155, v[8:11] offset:61440
	s_waitcnt vmcnt(13)
	ds_write_b128 v156, v[16:19] offset:40960
	s_waitcnt vmcnt(12)
	ds_write_b128 v156, v[24:27] offset:61440
	s_waitcnt vmcnt(11)
	ds_write_b128 v157, v[28:31] offset:40960
	s_waitcnt vmcnt(10)
	ds_write_b128 v157, v[36:39] offset:61440
	s_waitcnt vmcnt(9)
	ds_write_b128 v158, v[44:47] offset:40960
	s_waitcnt vmcnt(8)
	ds_write_b128 v158, v[56:59] offset:61440
	v_add_u32_e32 v44, v65, v142
	v_mov_b32_e32 v132, v44
	v_mul_lo_u32 v66, v146, s33
	v_lshl_add_u64 v[0:1], v[132:133], 1, s[88:89]
	v_add_u32_e32 v132, v65, v144
	global_load_dwordx4 v[0:3], v[0:1], off
	v_bfe_u32 v66, v66, 10, 6
	v_lshl_add_u64 v[8:9], v[132:133], 1, s[16:17]
	v_add_u32_e32 v132, 0x4000, v44
	global_load_dwordx4 v[8:11], v[8:9], off
	v_mul_lo_u32 v67, v66, -6
	v_lshl_add_u64 v[16:17], v[132:133], 1, s[88:89]
	v_add_u32_e32 v132, v65, v137
	global_load_dwordx4 v[16:19], v[16:17], off
	v_add_u32_e32 v151, v67, v146
	v_lshl_add_u64 v[24:25], v[132:133], 1, s[16:17]
	v_add_u32_e32 v132, 0x8000, v44
	global_load_dwordx4 v[24:27], v[24:25], off
	v_cmp_gt_i32_e32 vcc, 5, v151
	v_lshl_add_u64 v[28:29], v[132:133], 1, s[88:89]
	v_add_u32_e32 v132, v65, v148
	global_load_dwordx4 v[28:31], v[28:29], off
	v_cndmask_b32_e64 v67, 2, 1, vcc
	v_lshl_add_u64 v[36:37], v[132:133], 1, s[16:17]
	v_add_u32_e32 v132, 0xc000, v44
	global_load_dwordx4 v[36:39], v[36:37], off
	v_cmp_gt_i32_e64 s[8:9], 3, v151
	v_lshl_add_u64 v[44:45], v[132:133], 1, s[88:89]
	v_add_u32_e32 v132, v65, v149
	global_load_dwordx4 v[44:47], v[44:45], off
	v_cndmask_b32_e64 v152, v67, 0, s[8:9]
	v_lshl_add_u64 v[56:57], v[132:133], 1, s[16:17]
	global_load_dwordx4 v[56:59], v[56:57], off
	v_add_u32_e32 v64, v64, v145
	v_add_lshl_u32 v150, v64, v140, 9
	s_lshl_b32 s0, s92, 15
	v_lshlrev_b32_e32 v64, 20, v66
	v_lshlrev_b32_e32 v66, 18, v152
	s_and_b32 s0, s0, 0x38000
	v_or_b32_e32 v64, v66, v64
	v_or_b32_e32 v64, s0, v64
	v_add_u32_e32 v153, v64, v141
	v_and_b32_e32 v64, 15, v131
	v_bfe_u32 v159, v131, 4, 2
	v_ashrrev_i32_e32 v66, 1, v131
	s_movk_i32 s0, 0xffc0
	v_and_or_b32 v154, v66, s0, v64
	v_lshlrev_b32_e32 v64, 4, v159
	v_and_b32_e32 v66, 0x4f, v131
	s_movk_i32 s0, 0xa0
	v_mad_u64_u32 v[134:135], s[0:1], v154, s0, v[64:65]
	v_mul_u32_u24_e32 v66, 0x50, v66
	v_lshl_add_u32 v135, v66, 1, v64
	v_add_u32_e32 v64, v144, v143
	v_add_u32_e32 v164, v65, v64
	v_add_u32_e32 v166, v136, v64
	ds_read_b128 v[64:67], v134
	ds_read_b128 v[68:71], v134 offset:2560
	ds_read_b128 v[72:75], v135 offset:20480
	ds_read_b128 v[76:79], v135 offset:23040
	ds_read_b128 v[80:83], v134 offset:5120
	ds_read_b128 v[84:87], v134 offset:7680
	ds_read_b128 v[88:91], v135 offset:25600
	ds_read_b128 v[92:95], v135 offset:28160
	v_add_u32_e32 v162, v142, v136
	s_mov_b32 s12, 2
	s_mov_b32 s13, 0
	v_add_u32_e32 v160, 0xf000, v135
	v_add_u32_e32 v161, 0xf040, v135
	v_add_u32_e32 v163, 0x1c0, v162
	v_add_u32_e32 v165, 0x41c0, v162
	v_add_u32_e32 v167, 0x20c0, v166
	v_add_u32_e32 v168, 0x81c0, v162
	v_add_u32_e32 v169, 0x40c0, v166
	v_add_u32_e32 v170, 0xc1c0, v162
	v_add_u32_e32 v171, 0x60c0, v166
	v_add_u32_e32 v172, 0x2000, v153
	v_add_u32_e32 v173, 0x4000, v153
	v_add_u32_e32 v174, 0x6000, v153
	s_nop 0
	s_waitcnt lgkmcnt(5)
	v_mfma_f32_16x16x32_bf16 v[96:99], v[72:75], v[64:67], 0
	v_mfma_f32_16x16x32_bf16 v[100:103], v[72:75], v[68:71], 0
	s_waitcnt lgkmcnt(3)
	v_mfma_f32_16x16x32_bf16 v[104:107], v[72:75], v[80:83], 0
	s_waitcnt lgkmcnt(2)
	v_mfma_f32_16x16x32_bf16 v[72:75], v[72:75], v[84:87], 0
	v_mfma_f32_16x16x32_bf16 v[108:111], v[76:79], v[64:67], 0
	v_mfma_f32_16x16x32_bf16 v[112:115], v[76:79], v[68:71], 0
	v_mfma_f32_16x16x32_bf16 v[116:119], v[76:79], v[80:83], 0
	v_mfma_f32_16x16x32_bf16 v[76:79], v[76:79], v[84:87], 0
	s_waitcnt lgkmcnt(1)
	v_mfma_f32_16x16x32_bf16 v[120:123], v[88:91], v[64:67], 0
	v_mfma_f32_16x16x32_bf16 v[124:127], v[88:91], v[68:71], 0
	v_mfma_f32_16x16x32_bf16 v[176:179], v[88:91], v[80:83], 0
	v_mfma_f32_16x16x32_bf16 v[88:91], v[88:91], v[84:87], 0
	s_waitcnt lgkmcnt(0)
	v_mfma_f32_16x16x32_bf16 v[64:67], v[92:95], v[64:67], 0
	v_mfma_f32_16x16x32_bf16 v[68:71], v[92:95], v[68:71], 0
	v_mfma_f32_16x16x32_bf16 v[80:83], v[92:95], v[80:83], 0
	v_mfma_f32_16x16x32_bf16 v[84:87], v[92:95], v[84:87], 0
	s_nop 0
	ds_read_b128 v[92:95], v134 offset:64
	ds_read_b128 v[180:183], v134 offset:2624
	ds_read_b128 v[184:187], v135 offset:20544
	ds_read_b128 v[188:191], v135 offset:23104
	ds_read_b128 v[192:195], v134 offset:5184
	ds_read_b128 v[196:199], v134 offset:7744
	ds_read_b128 v[200:203], v135 offset:25664
	ds_read_b128 v[204:207], v135 offset:28224
	s_nop 0
	s_waitcnt lgkmcnt(5)
	v_mfma_f32_16x16x32_bf16 v[96:99], v[184:187], v[92:95], v[96:99]
	v_mfma_f32_16x16x32_bf16 v[100:103], v[184:187], v[180:183], v[100:103]
	s_waitcnt lgkmcnt(3)
	v_mfma_f32_16x16x32_bf16 v[104:107], v[184:187], v[192:195], v[104:107]
	s_waitcnt lgkmcnt(2)
	v_mfma_f32_16x16x32_bf16 v[72:75], v[184:187], v[196:199], v[72:75]
	v_mfma_f32_16x16x32_bf16 v[108:111], v[188:191], v[92:95], v[108:111]
	v_mfma_f32_16x16x32_bf16 v[112:115], v[188:191], v[180:183], v[112:115]
	v_mfma_f32_16x16x32_bf16 v[116:119], v[188:191], v[192:195], v[116:119]
	v_mfma_f32_16x16x32_bf16 v[76:79], v[188:191], v[196:199], v[76:79]
	s_waitcnt lgkmcnt(1)
	v_mfma_f32_16x16x32_bf16 v[120:123], v[200:203], v[92:95], v[120:123]
	v_mfma_f32_16x16x32_bf16 v[124:127], v[200:203], v[180:183], v[124:127]
	v_mfma_f32_16x16x32_bf16 v[88:91], v[200:203], v[196:199], v[88:91]
	s_waitcnt lgkmcnt(0)
	v_mfma_f32_16x16x32_bf16 v[64:67], v[204:207], v[92:95], v[64:67]
	v_mfma_f32_16x16x32_bf16 v[68:71], v[204:207], v[180:183], v[68:71]
	v_mfma_f32_16x16x32_bf16 v[80:83], v[204:207], v[192:195], v[80:83]
	v_mfma_f32_16x16x32_bf16 v[84:87], v[204:207], v[196:199], v[84:87]
	v_mfma_f32_16x16x32_bf16 v[176:179], v[200:203], v[192:195], v[176:179]
	s_nop 0
	v_add_u32_e32 v132, 0x100, v162
	s_barrier
	s_waitcnt vmcnt(15)
	ds_write_b128 v155, v[4:7]
	s_waitcnt vmcnt(14)
	ds_write_b128 v155, v[12:15] offset:20480
	s_waitcnt vmcnt(13)
	ds_write_b128 v156, v[20:23]
	s_waitcnt vmcnt(12)
	ds_write_b128 v156, v[32:35] offset:20480
	s_waitcnt vmcnt(11)
	ds_write_b128 v157, v[40:43]
	s_waitcnt vmcnt(10)
	ds_write_b128 v157, v[48:51] offset:20480
	s_waitcnt vmcnt(9)
	ds_write_b128 v158, v[52:55]
	s_waitcnt vmcnt(8)
	ds_write_b128 v158, v[60:63] offset:20480
	s_nop 0
	v_lshl_add_u64 v[4:5], v[132:133], 1, s[88:89]
	v_mov_b32_e32 v132, v166
	global_load_dwordx4 v[4:7], v[4:5], off
	s_nop 0
	v_lshl_add_u64 v[12:13], v[132:133], 1, s[16:17]
	v_add_u32_e32 v132, 0x4100, v162
	global_load_dwordx4 v[12:15], v[12:13], off
	s_nop 0
	v_lshl_add_u64 v[20:21], v[132:133], 1, s[88:89]
	v_add_u32_e32 v132, 0x2000, v166
	global_load_dwordx4 v[20:23], v[20:21], off
	s_nop 0
	v_lshl_add_u64 v[32:33], v[132:133], 1, s[16:17]
	v_add_u32_e32 v132, 0x8100, v162
	global_load_dwordx4 v[32:35], v[32:33], off
	s_nop 0
	v_lshl_add_u64 v[40:41], v[132:133], 1, s[88:89]
	v_add_u32_e32 v132, 0x4000, v166
	global_load_dwordx4 v[40:43], v[40:41], off
	s_nop 0
	v_lshl_add_u64 v[48:49], v[132:133], 1, s[16:17]
	v_add_u32_e32 v132, 0xc100, v162
	global_load_dwordx4 v[48:51], v[48:49], off
	s_nop 0
	v_lshl_add_u64 v[52:53], v[132:133], 1, s[88:89]
	v_add_u32_e32 v132, 0x6000, v166
	global_load_dwordx4 v[52:55], v[52:53], off
	s_nop 0
	v_lshl_add_u64 v[60:61], v[132:133], 1, s[16:17]
	global_load_dwordx4 v[60:63], v[60:61], off
	ds_read_b128 v[92:95], v134 offset:40960
	ds_read_b128 v[180:183], v134 offset:43520
	ds_read_b128 v[184:187], v135 offset:61440
	ds_read_b128 v[188:191], v135 offset:64000
	ds_read_b128 v[192:195], v134 offset:46080
	ds_read_b128 v[196:199], v134 offset:48640
	ds_read_b128 v[200:203], v160 offset:5120
	ds_read_b128 v[204:207], v160 offset:7680
	s_nop 0
	s_waitcnt lgkmcnt(5)
	v_mfma_f32_16x16x32_bf16 v[96:99], v[184:187], v[92:95], v[96:99]
	v_mfma_f32_16x16x32_bf16 v[100:103], v[184:187], v[180:183], v[100:103]
	s_waitcnt lgkmcnt(3)
	v_mfma_f32_16x16x32_bf16 v[104:107], v[184:187], v[192:195], v[104:107]
	s_waitcnt lgkmcnt(2)
	v_mfma_f32_16x16x32_bf16 v[72:75], v[184:187], v[196:199], v[72:75]
	v_mfma_f32_16x16x32_bf16 v[112:115], v[188:191], v[180:183], v[112:115]
	v_mfma_f32_16x16x32_bf16 v[116:119], v[188:191], v[192:195], v[116:119]
	s_waitcnt lgkmcnt(0)
	v_mfma_f32_16x16x32_bf16 v[64:67], v[204:207], v[92:95], v[64:67]
	v_mfma_f32_16x16x32_bf16 v[80:83], v[204:207], v[192:195], v[80:83]
	v_mfma_f32_16x16x32_bf16 v[184:187], v[188:191], v[92:95], v[108:111]
	v_mfma_f32_16x16x32_bf16 v[188:191], v[188:191], v[196:199], v[76:79]
	v_mfma_f32_16x16x32_bf16 v[208:211], v[200:203], v[92:95], v[120:123]
	v_mfma_f32_16x16x32_bf16 v[212:215], v[200:203], v[180:183], v[124:127]
	v_mfma_f32_16x16x32_bf16 v[176:179], v[200:203], v[192:195], v[176:179]
	v_mfma_f32_16x16x32_bf16 v[200:203], v[200:203], v[196:199], v[88:91]
	v_mfma_f32_16x16x32_bf16 v[180:183], v[204:207], v[180:183], v[68:71]
	v_mfma_f32_16x16x32_bf16 v[192:195], v[204:207], v[196:199], v[84:87]
	s_nop 0
	ds_read_b128 v[196:199], v134 offset:41024
	ds_read_b128 v[204:207], v134 offset:43584
	ds_read_b128 v[68:71], v135 offset:61504
	ds_read_b128 v[84:87], v135 offset:64064
	ds_read_b128 v[216:219], v134 offset:46144
	ds_read_b128 v[220:223], v134 offset:48704
	ds_read_b128 v[224:227], v161 offset:5120
	ds_read_b128 v[228:231], v161 offset:7680
	s_nop 0
	s_waitcnt lgkmcnt(5)
	v_mfma_f32_16x16x32_bf16 v[124:127], v[68:71], v[196:199], v[96:99]
	v_mfma_f32_16x16x32_bf16 v[108:111], v[68:71], v[204:207], v[100:103]
	s_waitcnt lgkmcnt(3)
	v_mfma_f32_16x16x32_bf16 v[92:95], v[68:71], v[216:219], v[104:107]
	s_waitcnt lgkmcnt(2)
	v_mfma_f32_16x16x32_bf16 v[76:79], v[68:71], v[220:223], v[72:75]
	v_mfma_f32_16x16x32_bf16 v[120:123], v[84:87], v[196:199], v[184:187]
	v_mfma_f32_16x16x32_bf16 v[104:107], v[84:87], v[204:207], v[112:115]
	v_mfma_f32_16x16x32_bf16 v[88:91], v[84:87], v[216:219], v[116:119]
	v_mfma_f32_16x16x32_bf16 v[72:75], v[84:87], v[220:223], v[188:191]
	s_waitcnt lgkmcnt(1)
	v_mfma_f32_16x16x32_bf16 v[116:119], v[224:227], v[196:199], v[208:211]
	v_mfma_f32_16x16x32_bf16 v[100:103], v[224:227], v[204:207], v[212:215]
	v_mfma_f32_16x16x32_bf16 v[84:87], v[224:227], v[216:219], v[176:179]
	v_mfma_f32_16x16x32_bf16 v[68:71], v[224:227], v[220:223], v[200:203]
	s_waitcnt lgkmcnt(0)
	v_mfma_f32_16x16x32_bf16 v[112:115], v[228:231], v[196:199], v[64:67]
	v_mfma_f32_16x16x32_bf16 v[96:99], v[228:231], v[204:207], v[180:183]
	v_mfma_f32_16x16x32_bf16 v[80:83], v[228:231], v[216:219], v[80:83]
	v_mfma_f32_16x16x32_bf16 v[64:67], v[228:231], v[220:223], v[192:195]
	s_nop 0
	v_add_u32_e32 v175, v150, v136
	s_branch .LBB0_1969
.LBB0_1968:
	s_waitcnt vmcnt(15)
	v_lshl_add_u64 v[60:61], v[132:133], 1, s[16:17]
	global_load_dwordx4 v[60:63], v[60:61], off
	ds_read_b128 v[176:179], v134 offset:40960
	ds_read_b128 v[180:183], v134 offset:43520
	ds_read_b128 v[184:187], v135 offset:61440
	ds_read_b128 v[188:191], v135 offset:64000
	ds_read_b128 v[192:195], v134 offset:46080
	ds_read_b128 v[196:199], v134 offset:48640
	ds_read_b128 v[200:203], v160 offset:5120
	ds_read_b128 v[204:207], v160 offset:7680
	s_nop 0
	s_waitcnt lgkmcnt(5)
	v_mfma_f32_16x16x32_bf16 v[64:67], v[184:187], v[176:179], v[64:67]
	v_mfma_f32_16x16x32_bf16 v[68:71], v[184:187], v[180:183], v[68:71]
	s_waitcnt lgkmcnt(3)
	v_mfma_f32_16x16x32_bf16 v[72:75], v[184:187], v[192:195], v[72:75]
	s_waitcnt lgkmcnt(2)
	v_mfma_f32_16x16x32_bf16 v[76:79], v[184:187], v[196:199], v[76:79]
	v_mfma_f32_16x16x32_bf16 v[80:83], v[188:191], v[176:179], v[80:83]
	v_mfma_f32_16x16x32_bf16 v[84:87], v[188:191], v[180:183], v[84:87]
	v_mfma_f32_16x16x32_bf16 v[88:91], v[188:191], v[192:195], v[88:91]
	s_waitcnt lgkmcnt(1)
	v_mfma_f32_16x16x32_bf16 v[96:99], v[200:203], v[176:179], v[96:99]
	v_mfma_f32_16x16x32_bf16 v[100:103], v[200:203], v[180:183], v[100:103]
	s_waitcnt lgkmcnt(0)
	v_mfma_f32_16x16x32_bf16 v[112:115], v[204:207], v[176:179], v[112:115]
	v_mfma_f32_16x16x32_bf16 v[184:187], v[188:191], v[196:199], v[92:95]
	v_mfma_f32_16x16x32_bf16 v[188:191], v[200:203], v[192:195], v[104:107]
	v_mfma_f32_16x16x32_bf16 v[200:203], v[200:203], v[196:199], v[108:111]
	v_mfma_f32_16x16x32_bf16 v[176:179], v[204:207], v[180:183], v[116:119]
	v_mfma_f32_16x16x32_bf16 v[180:183], v[204:207], v[192:195], v[120:123]
	v_mfma_f32_16x16x32_bf16 v[192:195], v[204:207], v[196:199], v[124:127]
	s_nop 0
	ds_read_b128 v[196:199], v134 offset:41024
	ds_read_b128 v[204:207], v134 offset:43584
	ds_read_b128 v[104:107], v135 offset:61504
	ds_read_b128 v[116:119], v135 offset:64064
	ds_read_b128 v[208:211], v134 offset:46144
	ds_read_b128 v[212:215], v134 offset:48704
	ds_read_b128 v[216:219], v161 offset:5120
	ds_read_b128 v[220:223], v161 offset:7680
	s_nop 0
	s_waitcnt lgkmcnt(5)
	v_mfma_f32_16x16x32_bf16 v[124:127], v[104:107], v[196:199], v[64:67]
	v_mfma_f32_16x16x32_bf16 v[108:111], v[104:107], v[204:207], v[68:71]
	s_waitcnt lgkmcnt(3)
	v_mfma_f32_16x16x32_bf16 v[92:95], v[104:107], v[208:211], v[72:75]
	s_waitcnt lgkmcnt(2)
	v_mfma_f32_16x16x32_bf16 v[76:79], v[104:107], v[212:215], v[76:79]
	v_mfma_f32_16x16x32_bf16 v[120:123], v[116:119], v[196:199], v[80:83]
	v_mfma_f32_16x16x32_bf16 v[104:107], v[116:119], v[204:207], v[84:87]
	v_mfma_f32_16x16x32_bf16 v[88:91], v[116:119], v[208:211], v[88:91]
	v_mfma_f32_16x16x32_bf16 v[72:75], v[116:119], v[212:215], v[184:187]
	s_waitcnt lgkmcnt(1)
	v_mfma_f32_16x16x32_bf16 v[116:119], v[216:219], v[196:199], v[96:99]
	v_mfma_f32_16x16x32_bf16 v[100:103], v[216:219], v[204:207], v[100:103]
	v_mfma_f32_16x16x32_bf16 v[84:87], v[216:219], v[208:211], v[188:191]
	v_mfma_f32_16x16x32_bf16 v[68:71], v[216:219], v[212:215], v[200:203]
	s_waitcnt lgkmcnt(0)
	v_mfma_f32_16x16x32_bf16 v[112:115], v[220:223], v[196:199], v[112:115]
	v_mfma_f32_16x16x32_bf16 v[96:99], v[220:223], v[204:207], v[176:179]
	v_mfma_f32_16x16x32_bf16 v[80:83], v[220:223], v[208:211], v[180:183]
	v_mfma_f32_16x16x32_bf16 v[64:67], v[220:223], v[212:215], v[192:195]
	s_nop 0
	s_add_i32 s12, s12, 2
	s_addk_i32 s13, 0x80
	s_and_b64 vcc, exec, s[0:1]
	s_cbranch_vccnz .LBB0_1987

.LBB0_1977:
	s_nop 0
	v_lshl_add_u64 v[56:57], v[132:133], 1, s[16:17]
	global_load_dwordx4 v[56:59], v[56:57], off
	ds_read_b128 v[178:181], v134
	ds_read_b128 v[182:185], v134 offset:2560
	ds_read_b128 v[186:189], v135 offset:20480
	ds_read_b128 v[190:193], v135 offset:23040
	ds_read_b128 v[194:197], v134 offset:5120
	ds_read_b128 v[198:201], v134 offset:7680
	ds_read_b128 v[202:205], v135 offset:25600
	ds_read_b128 v[206:209], v135 offset:28160
	s_nop 0
	s_waitcnt lgkmcnt(5)
	v_mfma_f32_16x16x32_bf16 v[124:127], v[186:189], v[178:181], v[124:127]
	v_mfma_f32_16x16x32_bf16 v[108:111], v[186:189], v[182:185], v[108:111]
	s_waitcnt lgkmcnt(3)
	v_mfma_f32_16x16x32_bf16 v[92:95], v[186:189], v[194:197], v[92:95]
	s_waitcnt lgkmcnt(2)
	v_mfma_f32_16x16x32_bf16 v[76:79], v[186:189], v[198:201], v[76:79]
	v_mfma_f32_16x16x32_bf16 v[120:123], v[190:193], v[178:181], v[120:123]
	v_mfma_f32_16x16x32_bf16 v[104:107], v[190:193], v[182:185], v[104:107]
	v_mfma_f32_16x16x32_bf16 v[88:91], v[190:193], v[194:197], v[88:91]
	s_waitcnt lgkmcnt(1)
	v_mfma_f32_16x16x32_bf16 v[116:119], v[202:205], v[178:181], v[116:119]
	v_mfma_f32_16x16x32_bf16 v[100:103], v[202:205], v[182:185], v[100:103]
	s_waitcnt lgkmcnt(0)
	v_mfma_f32_16x16x32_bf16 v[112:115], v[206:209], v[178:181], v[112:115]
	v_mfma_f32_16x16x32_bf16 v[186:189], v[190:193], v[198:201], v[72:75]
	v_mfma_f32_16x16x32_bf16 v[190:193], v[202:205], v[194:197], v[84:87]
	v_mfma_f32_16x16x32_bf16 v[202:205], v[202:205], v[198:201], v[68:71]
	v_mfma_f32_16x16x32_bf16 v[178:181], v[206:209], v[182:185], v[96:99]
	v_mfma_f32_16x16x32_bf16 v[182:185], v[206:209], v[194:197], v[80:83]
	v_mfma_f32_16x16x32_bf16 v[194:197], v[206:209], v[198:201], v[64:67]
	s_nop 0
	ds_read_b128 v[198:201], v134 offset:64
	ds_read_b128 v[206:209], v134 offset:2624
	ds_read_b128 v[80:83], v135 offset:20544
	ds_read_b128 v[96:99], v135 offset:23104
	ds_read_b128 v[210:213], v134 offset:5184
	ds_read_b128 v[214:217], v134 offset:7744
	ds_read_b128 v[218:221], v135 offset:25664
	ds_read_b128 v[222:225], v135 offset:28224
	s_nop 0
	s_waitcnt lgkmcnt(5)
	v_mfma_f32_16x16x32_bf16 v[64:67], v[80:83], v[198:201], v[124:127]
	v_mfma_f32_16x16x32_bf16 v[68:71], v[80:83], v[206:209], v[108:111]
	s_waitcnt lgkmcnt(3)
	v_mfma_f32_16x16x32_bf16 v[72:75], v[80:83], v[210:213], v[92:95]
	s_waitcnt lgkmcnt(2)
	v_mfma_f32_16x16x32_bf16 v[76:79], v[80:83], v[214:217], v[76:79]
	v_mfma_f32_16x16x32_bf16 v[80:83], v[96:99], v[198:201], v[120:123]
	v_mfma_f32_16x16x32_bf16 v[84:87], v[96:99], v[206:209], v[104:107]
	v_mfma_f32_16x16x32_bf16 v[88:91], v[96:99], v[210:213], v[88:91]
	v_mfma_f32_16x16x32_bf16 v[92:95], v[96:99], v[214:217], v[186:189]
	s_waitcnt lgkmcnt(1)
	v_mfma_f32_16x16x32_bf16 v[96:99], v[218:221], v[198:201], v[116:119]
	v_mfma_f32_16x16x32_bf16 v[100:103], v[218:221], v[206:209], v[100:103]
	v_mfma_f32_16x16x32_bf16 v[104:107], v[218:221], v[210:213], v[190:193]
	v_mfma_f32_16x16x32_bf16 v[108:111], v[218:221], v[214:217], v[202:205]
	s_waitcnt lgkmcnt(0)
	v_mfma_f32_16x16x32_bf16 v[112:115], v[222:225], v[198:201], v[112:115]
	v_mfma_f32_16x16x32_bf16 v[116:119], v[222:225], v[206:209], v[178:181]
	v_mfma_f32_16x16x32_bf16 v[120:123], v[222:225], v[210:213], v[182:185]
	v_mfma_f32_16x16x32_bf16 v[124:127], v[222:225], v[214:217], v[194:197]
	s_nop 0
	s_cmp_gt_u32 s12, 5
	s_cselect_b64 s[0:1], -1, 0
	s_cmp_lt_u32 s12, 6
	s_cselect_b64 s[10:11], -1, 0
	s_or_b64 s[10:11], s[6:7], s[10:11]
	s_andn2_b64 vcc, exec, s[10:11]
	s_barrier
	s_cbranch_vccnz .LBB0_1979
	s_waitcnt vmcnt(15)
	ds_write_b128 v155, v[4:7]
	s_waitcnt vmcnt(14)
	ds_write_b128 v155, v[12:15] offset:20480
	s_waitcnt vmcnt(13)
	ds_write_b128 v156, v[20:23]
	s_waitcnt vmcnt(12)
	ds_write_b128 v156, v[32:35] offset:20480
	s_waitcnt vmcnt(11)
	ds_write_b128 v157, v[40:43]
	s_waitcnt vmcnt(10)
	ds_write_b128 v157, v[48:51] offset:20480
	s_waitcnt vmcnt(9)
	ds_write_b128 v158, v[52:55]
	s_waitcnt vmcnt(8)
	ds_write_b128 v158, v[60:63] offset:20480
